# v36: v33 + GEMM main loops: counter/pointer bumps and exit compare moved in front of the loop-back barrier (only the branch stays after it)
# speedup vs baseline: 1.0021x; 1.0004x over previous
; #define PG8_STAGE(bufoff, gbase, voff) do { _Pragma("unroll") for (int _i = 0; _i < 2; ++_i) \
;         __builtin_amdgcn_global_load_lds((const unsigned*)((const char*)(gbase) + (voff)[_i]), (LAS unsigned*)(lds + (bufoff) + ldsw + _i * 8192), 16, 0, 0); } while (0)
; #define PG8_LDA(dst, b, h) do { _Pragma("unroll") for (int m = 0; m < 4; ++m) _Pragma("unroll") for (int k = 0; k < 2; ++k) dst[m][k] = *(const LAS bf16x8*)(lds + PG8_SA(b, h) + aoff + m * 2048 + k * 1024); } while (0)
; #define PG8_LDB(dst, b, h) do { _Pragma("unroll") for (int n = 0; n < 2; ++n) _Pragma("unroll") for (int k = 0; k < 2; ++k) dst[n][k] = *(const LAS bf16x8*)(lds + PG8_SB(b, h) + boff + n * 2048 + k * 1024); } while (0)
; #define PG8_MMA(ai, bj, At, Bt) do { __builtin_amdgcn_s_setprio(1); _Pragma("unroll") for (int m = 0; m < 4; ++m) _Pragma("unroll") for (int n = 0; n < 2; ++n) _Pragma("unroll") for (int k = 0; k < 2; ++k) \
;         acc[ai][bj][m][n] = __builtin_amdgcn_mfma_f32_16x16x32_bf16(Bt[n][k], At[m][k], acc[ai][bj][m][n], 0, 0, 0); __builtin_amdgcn_s_setprio(0); } while (0)
; #define PG8_WAIT_V(n) asm volatile("s_waitcnt vmcnt(" #n ")" ::: "memory")
; #define PG8_WAIT_L(n) asm volatile("s_waitcnt lgkmcnt(" #n ")" ::: "memory")
; #define PG8_BAR __builtin_amdgcn_s_barrier()
; #define PG8_SCHED __builtin_amdgcn_sched_barrier(0)
; template <class Epi, class Sched>
; __device__ __forceinline__ void gemm_phase(LAS unsigned char* lds, const Gemm g, const Sched& S, const Epi& E) {
;     ...
;             PG8_LDB(B0, 0, 0); PG8_LDB(B1, 0, 1); PG8_SCHED; PG8_LDA(At, 0, 0); PG8_STAGE(PG8_SA(1, 1), a1 + hstepA, voffA);
;             PG8_WAIT_V(8); PG8_WAIT_L(0); PG8_BAR; PG8_MMA(0, 0, At, B0); PG8_MMA(0, 1, At, B1); PG8_BAR; PG8_SCHED;
;             PG8_LDA(At, 0, 1); PG8_STAGE(PG8_SB(0, 0), b2, voffB); PG8_STAGE(PG8_SB(0, 1), b2 + hstepB, voffB); PG8_STAGE(PG8_SA(0, 0), a2, voffA);
;             PG8_WAIT_V(8); PG8_WAIT_L(0); PG8_BAR; PG8_MMA(1, 0, At, B0); PG8_MMA(1, 1, At, B1); PG8_BAR; PG8_SCHED;
.LBB0_141:
	ds_read_b128 v[150:153], v147
	ds_read_b128 v[154:157], v147 offset:1024
	ds_read_b128 v[158:161], v147 offset:2048
	ds_read_b128 v[162:165], v147 offset:3072
	ds_read_b128 v[166:169], v148
	ds_read_b128 v[170:173], v148 offset:1024
	ds_read_b128 v[174:177], v148 offset:2048
	ds_read_b128 v[178:181], v148 offset:3072
	s_add_u32 s16, s54, 0xfff80080
	s_addc_u32 s17, s55, -1
	s_cmp_eq_u32 s79, 28
	s_cselect_b32 s59, s49, s17
	s_cselect_b32 s58, s75, s16
	s_cselect_b32 s57, s47, s78
	s_cselect_b32 s56, s76, s77
	v_lshl_add_u64 v[190:191], s[54:55], 0, v[136:137]
	s_add_i32 m0, s45, 0xc000
	ds_read_b128 v[182:185], v149
	ds_read_b128 v[186:189], v149 offset:1024
	ds_read_b128 v[196:199], v149 offset:2048
	ds_read_b128 v[200:203], v149 offset:3072
	ds_read_b128 v[208:211], v149 offset:4096
	ds_read_b128 v[212:215], v149 offset:5120
	ds_read_b128 v[216:219], v149 offset:6144
	ds_read_b128 v[220:223], v149 offset:7168
	global_load_lds_dwordx4 v[190:191], off
	v_lshl_add_u64 v[190:191], s[54:55], 0, v[138:139]
	s_add_i32 m0, s45, 0xe000
	s_nop 0
	global_load_lds_dwordx4 v[190:191], off
	s_waitcnt vmcnt(8)
	s_waitcnt lgkmcnt(0)
	s_barrier
	s_setprio 1
	s_waitcnt lgkmcnt(0)
	v_mfma_f32_16x16x32_bf16 v[124:127], v[150:153], v[182:185], v[124:127]
	v_mfma_f32_16x16x32_bf16 v[120:123], v[158:161], v[182:185], v[120:123]
	v_mfma_f32_16x16x32_bf16 v[116:119], v[150:153], v[196:199], v[116:119]
	v_mfma_f32_16x16x32_bf16 v[112:115], v[158:161], v[196:199], v[112:115]
	v_mfma_f32_16x16x32_bf16 v[100:103], v[150:153], v[208:211], v[100:103]
	v_mfma_f32_16x16x32_bf16 v[96:99], v[158:161], v[208:211], v[96:99]
	v_mfma_f32_16x16x32_bf16 v[84:87], v[150:153], v[216:219], v[84:87]
	v_mfma_f32_16x16x32_bf16 v[80:83], v[158:161], v[216:219], v[80:83]
	v_mfma_f32_16x16x32_bf16 v[124:127], v[154:157], v[186:189], v[124:127]
	v_mfma_f32_16x16x32_bf16 v[120:123], v[162:165], v[186:189], v[120:123]
	v_mfma_f32_16x16x32_bf16 v[116:119], v[154:157], v[200:203], v[116:119]
	v_mfma_f32_16x16x32_bf16 v[112:115], v[162:165], v[200:203], v[112:115]
	v_mfma_f32_16x16x32_bf16 v[100:103], v[154:157], v[212:215], v[100:103]
	v_mfma_f32_16x16x32_bf16 v[96:99], v[162:165], v[212:215], v[96:99]
	v_mfma_f32_16x16x32_bf16 v[84:87], v[154:157], v[220:223], v[84:87]
	v_mfma_f32_16x16x32_bf16 v[80:83], v[162:165], v[220:223], v[80:83]
	s_setprio 0
	s_setprio 1
	v_mfma_f32_16x16x32_bf16 v[108:111], v[166:169], v[182:185], v[108:111]
	v_mfma_f32_16x16x32_bf16 v[104:107], v[174:177], v[182:185], v[104:107]
	v_mfma_f32_16x16x32_bf16 v[92:95], v[166:169], v[196:199], v[92:95]
	v_mfma_f32_16x16x32_bf16 v[88:91], v[174:177], v[196:199], v[88:91]
	v_mfma_f32_16x16x32_bf16 v[76:79], v[166:169], v[208:211], v[76:79]
	v_mfma_f32_16x16x32_bf16 v[72:75], v[174:177], v[208:211], v[72:75]
	v_mfma_f32_16x16x32_bf16 v[68:71], v[166:169], v[216:219], v[68:71]
	v_mfma_f32_16x16x32_bf16 v[64:67], v[174:177], v[216:219], v[64:67]
	v_mfma_f32_16x16x32_bf16 v[108:111], v[170:173], v[186:189], v[108:111]
	v_mfma_f32_16x16x32_bf16 v[104:107], v[178:181], v[186:189], v[104:107]
	v_mfma_f32_16x16x32_bf16 v[92:95], v[170:173], v[200:203], v[92:95]
	v_mfma_f32_16x16x32_bf16 v[88:91], v[178:181], v[200:203], v[88:91]
	v_mfma_f32_16x16x32_bf16 v[76:79], v[170:173], v[212:215], v[76:79]
	v_mfma_f32_16x16x32_bf16 v[72:75], v[178:181], v[212:215], v[72:75]
	v_mfma_f32_16x16x32_bf16 v[68:71], v[170:173], v[220:223], v[68:71]
	v_mfma_f32_16x16x32_bf16 v[64:67], v[178:181], v[220:223], v[64:67]
	s_setprio 0
	s_barrier
	s_add_i32 s16, s68, s60
	v_lshl_add_u64 v[190:191], s[56:57], 0, v[130:131]
	s_mov_b32 m0, s16
	ds_read_b128 v[182:185], v149 offset:16384
	ds_read_b128 v[186:189], v149 offset:17408
	ds_read_b128 v[196:199], v149 offset:18432
	ds_read_b128 v[200:203], v149 offset:19456
	ds_read_b128 v[208:211], v149 offset:20480
	ds_read_b128 v[212:215], v149 offset:21504
	ds_read_b128 v[216:219], v149 offset:22528
	ds_read_b128 v[220:223], v149 offset:23552
	global_load_lds_dwordx4 v[190:191], off
	s_add_i32 m0, s16, 0x2000
	s_add_u32 s34, s56, 0x80000
	v_lshl_add_u64 v[204:205], s[56:57], 0, v[134:135]
	s_addc_u32 s35, s57, 0
	s_add_i32 s16, s69, s60
	global_load_lds_dwordx4 v[204:205], off
	v_lshl_add_u64 v[224:225], s[34:35], 0, v[130:131]
	s_mov_b32 m0, s16
	v_lshl_add_u64 v[226:227], s[58:59], 0, v[132:133]
	global_load_lds_dwordx4 v[224:225], off
	v_lshl_add_u64 v[224:225], s[34:35], 0, v[134:135]
	s_add_i32 m0, s16, 0x2000
	s_nop 0
	global_load_lds_dwordx4 v[224:225], off
	v_lshl_add_u64 v[224:225], s[58:59], 0, v[128:129]
	s_mov_b32 m0, s45
	s_nop 0
	global_load_lds_dwordx4 v[224:225], off
	s_mov_b32 m0, s61
	s_nop 0
	global_load_lds_dwordx4 v[226:227], off
	s_waitcnt vmcnt(8)
	s_waitcnt lgkmcnt(0)
	s_barrier
; #define PG8_STAGE(bufoff, gbase, voff) do { _Pragma("unroll") for (int _i = 0; _i < 2; ++_i) \
;         __builtin_amdgcn_global_load_lds((const unsigned*)((const char*)(gbase) + (voff)[_i]), (LAS unsigned*)(lds + (bufoff) + ldsw + _i * 8192), 16, 0, 0); } while (0)
; #define PG8_LDA(dst, b, h) do { _Pragma("unroll") for (int m = 0; m < 4; ++m) _Pragma("unroll") for (int k = 0; k < 2; ++k) dst[m][k] = *(const LAS bf16x8*)(lds + PG8_SA(b, h) + aoff + m * 2048 + k * 1024); } while (0)
; #define PG8_LDB(dst, b, h) do { _Pragma("unroll") for (int n = 0; n < 2; ++n) _Pragma("unroll") for (int k = 0; k < 2; ++k) dst[n][k] = *(const LAS bf16x8*)(lds + PG8_SB(b, h) + boff + n * 2048 + k * 1024); } while (0)
; #define PG8_MMA(ai, bj, At, Bt) do { __builtin_amdgcn_s_setprio(1); _Pragma("unroll") for (int m = 0; m < 4; ++m) _Pragma("unroll") for (int n = 0; n < 2; ++n) _Pragma("unroll") for (int k = 0; k < 2; ++k) \
;         acc[ai][bj][m][n] = __builtin_amdgcn_mfma_f32_16x16x32_bf16(Bt[n][k], At[m][k], acc[ai][bj][m][n], 0, 0, 0); __builtin_amdgcn_s_setprio(0); } while (0)
; #define PG8_WAIT_V(n) asm volatile("s_waitcnt vmcnt(" #n ")" ::: "memory")
; #define PG8_WAIT_L(n) asm volatile("s_waitcnt lgkmcnt(" #n ")" ::: "memory")
; #define PG8_BAR __builtin_amdgcn_s_barrier()
; #define PG8_SCHED __builtin_amdgcn_sched_barrier(0)
; template <class Epi, class Sched>
; __device__ __forceinline__ void gemm_phase(LAS unsigned char* lds, const Gemm g, const Sched& S, const Epi& E) {
;     ...
;             PG8_WAIT_V(8); PG8_WAIT_L(0); PG8_BAR; PG8_MMA(1, 0, At, B0); PG8_MMA(1, 1, At, B1); PG8_BAR; PG8_SCHED;
;             PG8_LDB(B0, 1, 0); PG8_LDB(B1, 1, 1); PG8_SCHED; PG8_LDA(At, 1, 0); PG8_STAGE(PG8_SA(0, 1), a2 + hstepA, voffA);
;             PG8_WAIT_V(8); PG8_WAIT_L(0); PG8_BAR; PG8_MMA(0, 0, At, B0); PG8_MMA(0, 1, At, B1); PG8_BAR; PG8_SCHED;
;             PG8_LDA(At, 1, 1); PG8_STAGE(PG8_SB(1, 0), b3, voffB); PG8_STAGE(PG8_SB(1, 1), b3 + hstepB, voffB); PG8_STAGE(PG8_SA(1, 0), a3, voffA);
	s_setprio 1
	s_waitcnt lgkmcnt(0)
	v_mfma_f32_16x16x32_bf16 v[60:63], v[150:153], v[182:185], v[60:63]
	v_mfma_f32_16x16x32_bf16 v[56:59], v[158:161], v[182:185], v[56:59]
	v_mfma_f32_16x16x32_bf16 v[52:55], v[150:153], v[196:199], v[52:55]
	v_mfma_f32_16x16x32_bf16 v[48:51], v[158:161], v[196:199], v[48:51]
	v_mfma_f32_16x16x32_bf16 v[36:39], v[150:153], v[208:211], v[36:39]
	v_mfma_f32_16x16x32_bf16 v[32:35], v[158:161], v[208:211], v[32:35]
	v_mfma_f32_16x16x32_bf16 v[20:23], v[150:153], v[216:219], v[20:23]
	v_mfma_f32_16x16x32_bf16 v[16:19], v[158:161], v[216:219], v[16:19]
	v_mfma_f32_16x16x32_bf16 v[60:63], v[154:157], v[186:189], v[60:63]
	v_mfma_f32_16x16x32_bf16 v[56:59], v[162:165], v[186:189], v[56:59]
	v_mfma_f32_16x16x32_bf16 v[52:55], v[154:157], v[200:203], v[52:55]
	v_mfma_f32_16x16x32_bf16 v[48:51], v[162:165], v[200:203], v[48:51]
	v_mfma_f32_16x16x32_bf16 v[36:39], v[154:157], v[212:215], v[36:39]
	v_mfma_f32_16x16x32_bf16 v[32:35], v[162:165], v[212:215], v[32:35]
	v_mfma_f32_16x16x32_bf16 v[20:23], v[154:157], v[220:223], v[20:23]
	v_mfma_f32_16x16x32_bf16 v[16:19], v[162:165], v[220:223], v[16:19]
	s_setprio 0
	s_setprio 1
	v_mfma_f32_16x16x32_bf16 v[44:47], v[166:169], v[182:185], v[44:47]
	v_mfma_f32_16x16x32_bf16 v[40:43], v[174:177], v[182:185], v[40:43]
	v_mfma_f32_16x16x32_bf16 v[28:31], v[166:169], v[196:199], v[28:31]
	v_mfma_f32_16x16x32_bf16 v[24:27], v[174:177], v[196:199], v[24:27]
	v_mfma_f32_16x16x32_bf16 v[12:15], v[166:169], v[208:211], v[12:15]
	v_mfma_f32_16x16x32_bf16 v[8:11], v[174:177], v[208:211], v[8:11]
	v_mfma_f32_16x16x32_bf16 v[4:7], v[166:169], v[216:219], v[4:7]
	v_mfma_f32_16x16x32_bf16 v[0:3], v[174:177], v[216:219], v[0:3]
	v_mfma_f32_16x16x32_bf16 v[44:47], v[170:173], v[186:189], v[44:47]
	v_mfma_f32_16x16x32_bf16 v[40:43], v[178:181], v[186:189], v[40:43]
	v_mfma_f32_16x16x32_bf16 v[28:31], v[170:173], v[200:203], v[28:31]
	v_mfma_f32_16x16x32_bf16 v[24:27], v[178:181], v[200:203], v[24:27]
	v_mfma_f32_16x16x32_bf16 v[12:15], v[170:173], v[212:215], v[12:15]
	v_mfma_f32_16x16x32_bf16 v[8:11], v[178:181], v[212:215], v[8:11]
	v_mfma_f32_16x16x32_bf16 v[4:7], v[170:173], v[220:223], v[4:7]
	v_mfma_f32_16x16x32_bf16 v[0:3], v[178:181], v[220:223], v[0:3]
	s_setprio 0
	s_barrier
	s_add_i32 s16, 0, 0x18000
	s_add_i32 s17, 0, 0x1c000
	v_add_u32_e32 v162, s16, v145
	v_add_u32_e32 v178, s17, v145
	ds_read_b128 v[150:153], v162
	ds_read_b128 v[154:157], v162 offset:1024
	ds_read_b128 v[158:161], v162 offset:2048
	ds_read_b128 v[162:165], v162 offset:3072
	ds_read_b128 v[166:169], v178
	ds_read_b128 v[170:173], v178 offset:1024
	ds_read_b128 v[174:177], v178 offset:2048
	ds_read_b128 v[178:181], v178 offset:3072
	s_add_u32 s34, s58, 0x80000
	s_addc_u32 s35, s59, 0
	s_mov_b32 m0, s62
	v_lshl_add_u64 v[228:229], s[34:35], 0, v[128:129]
	ds_read_b128 v[182:185], v149 offset:32768
	ds_read_b128 v[186:189], v149 offset:33792
	ds_read_b128 v[196:199], v149 offset:34816
	ds_read_b128 v[200:203], v149 offset:35840
	ds_read_b128 v[208:211], v149 offset:36864
	ds_read_b128 v[212:215], v149 offset:37888
	ds_read_b128 v[216:219], v149 offset:38912
	ds_read_b128 v[220:223], v149 offset:39936
	global_load_lds_dwordx4 v[228:229], off
	v_lshl_add_u64 v[228:229], s[34:35], 0, v[132:133]
	s_mov_b32 m0, s63
	s_nop 0
	global_load_lds_dwordx4 v[228:229], off
	s_waitcnt vmcnt(8)
	s_waitcnt lgkmcnt(0)
	s_barrier
	s_setprio 1
	s_waitcnt lgkmcnt(0)
	v_mfma_f32_16x16x32_bf16 v[124:127], v[150:153], v[182:185], v[124:127]
	v_mfma_f32_16x16x32_bf16 v[120:123], v[158:161], v[182:185], v[120:123]
	v_mfma_f32_16x16x32_bf16 v[116:119], v[150:153], v[196:199], v[116:119]
	v_mfma_f32_16x16x32_bf16 v[112:115], v[158:161], v[196:199], v[112:115]
	v_mfma_f32_16x16x32_bf16 v[100:103], v[150:153], v[208:211], v[100:103]
	v_mfma_f32_16x16x32_bf16 v[96:99], v[158:161], v[208:211], v[96:99]
	v_mfma_f32_16x16x32_bf16 v[84:87], v[150:153], v[216:219], v[84:87]
	v_mfma_f32_16x16x32_bf16 v[80:83], v[158:161], v[216:219], v[80:83]
	v_mfma_f32_16x16x32_bf16 v[124:127], v[154:157], v[186:189], v[124:127]
	v_mfma_f32_16x16x32_bf16 v[120:123], v[162:165], v[186:189], v[120:123]
	v_mfma_f32_16x16x32_bf16 v[116:119], v[154:157], v[200:203], v[116:119]
	v_mfma_f32_16x16x32_bf16 v[112:115], v[162:165], v[200:203], v[112:115]
	v_mfma_f32_16x16x32_bf16 v[100:103], v[154:157], v[212:215], v[100:103]
	v_mfma_f32_16x16x32_bf16 v[96:99], v[162:165], v[212:215], v[96:99]
	v_mfma_f32_16x16x32_bf16 v[84:87], v[154:157], v[220:223], v[84:87]
	v_mfma_f32_16x16x32_bf16 v[80:83], v[162:165], v[220:223], v[80:83]
	s_setprio 0
	s_setprio 1
	v_mfma_f32_16x16x32_bf16 v[108:111], v[166:169], v[182:185], v[108:111]
	v_mfma_f32_16x16x32_bf16 v[104:107], v[174:177], v[182:185], v[104:107]
	v_mfma_f32_16x16x32_bf16 v[92:95], v[166:169], v[196:199], v[92:95]
	v_mfma_f32_16x16x32_bf16 v[88:91], v[174:177], v[196:199], v[88:91]
	v_mfma_f32_16x16x32_bf16 v[76:79], v[166:169], v[208:211], v[76:79]
	v_mfma_f32_16x16x32_bf16 v[72:75], v[174:177], v[208:211], v[72:75]
	v_mfma_f32_16x16x32_bf16 v[68:71], v[166:169], v[216:219], v[68:71]
	v_mfma_f32_16x16x32_bf16 v[64:67], v[174:177], v[216:219], v[64:67]
	v_mfma_f32_16x16x32_bf16 v[108:111], v[170:173], v[186:189], v[108:111]
	v_mfma_f32_16x16x32_bf16 v[104:107], v[178:181], v[186:189], v[104:107]
	v_mfma_f32_16x16x32_bf16 v[92:95], v[170:173], v[200:203], v[92:95]
	v_mfma_f32_16x16x32_bf16 v[88:91], v[178:181], v[200:203], v[88:91]
	v_mfma_f32_16x16x32_bf16 v[76:79], v[170:173], v[212:215], v[76:79]
	v_mfma_f32_16x16x32_bf16 v[72:75], v[178:181], v[212:215], v[72:75]
	v_mfma_f32_16x16x32_bf16 v[68:71], v[170:173], v[220:223], v[68:71]
	v_mfma_f32_16x16x32_bf16 v[64:67], v[178:181], v[220:223], v[64:67]
	s_setprio 0
	s_barrier
; #define PG8_STAGE(bufoff, gbase, voff) do { _Pragma("unroll") for (int _i = 0; _i < 2; ++_i) \
;         __builtin_amdgcn_global_load_lds((const unsigned*)((const char*)(gbase) + (voff)[_i]), (LAS unsigned*)(lds + (bufoff) + ldsw + _i * 8192), 16, 0, 0); } while (0)
; #define PG8_LDA(dst, b, h) do { _Pragma("unroll") for (int m = 0; m < 4; ++m) _Pragma("unroll") for (int k = 0; k < 2; ++k) dst[m][k] = *(const LAS bf16x8*)(lds + PG8_SA(b, h) + aoff + m * 2048 + k * 1024); } while (0)
; #define PG8_LDB(dst, b, h) do { _Pragma("unroll") for (int n = 0; n < 2; ++n) _Pragma("unroll") for (int k = 0; k < 2; ++k) dst[n][k] = *(const LAS bf16x8*)(lds + PG8_SB(b, h) + boff + n * 2048 + k * 1024); } while (0)
; #define PG8_WAIT_V(n) asm volatile("s_waitcnt vmcnt(" #n ")" ::: "memory")
; #define PG8_BAR __builtin_amdgcn_s_barrier()
; template <class Epi, class Sched>
; __device__ __forceinline__ void gemm_phase(LAS unsigned char* lds, const Gemm g, const Sched& S, const Epi& E) {
;     ...
;         for (int t = 0; t < nt; t += 2) {
;             const bool last = (t == nt - 2);
;             const char* a1 = cA + (size_t)(t + 1) * kstep;
;             const char* a2 = last ? nA : cA + (size_t)(t + 2) * kstep; const char* b2 = last ? nB : cB + (size_t)(t + 2) * kstep;
;             const char* a3 = a2 + kstep; const char* b3 = b2 + kstep;
;             PG8_LDB(B0, 0, 0); PG8_LDB(B1, 0, 1); PG8_SCHED; PG8_LDA(At, 0, 0); PG8_STAGE(PG8_SA(1, 1), a1 + hstepA, voffA);
;             PG8_WAIT_V(8); PG8_WAIT_L(0); PG8_BAR; PG8_MMA(0, 0, At, B0); PG8_MMA(0, 1, At, B1); PG8_BAR; PG8_SCHED;
;             PG8_LDA(At, 0, 1); PG8_STAGE(PG8_SB(0, 0), b2, voffB); PG8_STAGE(PG8_SB(0, 1), b2 + hstepB, voffB); PG8_STAGE(PG8_SA(0, 0), a2, voffA);
;             PG8_WAIT_V(8); PG8_WAIT_L(0); PG8_BAR; PG8_MMA(1, 0, At, B0); PG8_MMA(1, 1, At, B1); PG8_BAR; PG8_SCHED;
;             PG8_LDB(B0, 1, 0); PG8_LDB(B1, 1, 1); PG8_SCHED; PG8_LDA(At, 1, 0); PG8_STAGE(PG8_SA(0, 1), a2 + hstepA, voffA);
;             PG8_WAIT_V(8); PG8_WAIT_L(0); PG8_BAR; PG8_MMA(0, 0, At, B0); PG8_MMA(0, 1, At, B1); PG8_BAR; PG8_SCHED;
;             PG8_LDA(At, 1, 1); PG8_STAGE(PG8_SB(1, 0), b3, voffB); PG8_STAGE(PG8_SB(1, 1), b3 + hstepB, voffB); PG8_STAGE(PG8_SA(1, 0), a3, voffA);
;             PG8_WAIT_V(8); PG8_WAIT_L(0); PG8_BAR; PG8_MMA(1, 0, At, B0); PG8_MMA(1, 1, At, B1); PG8_BAR; PG8_SCHED;
	s_add_i32 s16, s16, s60
	v_lshl_add_u64 v[190:191], v[190:191], 0, s[10:11]
	s_mov_b32 m0, s16
	ds_read_b128 v[182:185], v149 offset:49152
	ds_read_b128 v[186:189], v149 offset:50176
	ds_read_b128 v[196:199], v149 offset:51200
	ds_read_b128 v[200:203], v149 offset:52224
	ds_read_b128 v[208:211], v149 offset:53248
	ds_read_b128 v[212:215], v149 offset:54272
	ds_read_b128 v[216:219], v149 offset:55296
	ds_read_b128 v[220:223], v149 offset:56320
	global_load_lds_dwordx4 v[190:191], off
	s_add_i32 m0, s16, 0x2000
	s_add_u32 s34, s56, 0x80080
	v_lshl_add_u64 v[190:191], v[204:205], 0, s[10:11]
	s_addc_u32 s35, s57, 0
	s_add_i32 s16, s17, s60
	global_load_lds_dwordx4 v[190:191], off
	v_lshl_add_u64 v[190:191], s[34:35], 0, v[130:131]
	s_mov_b32 m0, s16
	s_nop 0
	global_load_lds_dwordx4 v[190:191], off
	v_lshl_add_u64 v[190:191], s[34:35], 0, v[134:135]
	s_add_i32 m0, s16, 0x2000
	s_nop 0
	global_load_lds_dwordx4 v[190:191], off
	v_lshl_add_u64 v[190:191], v[224:225], 0, s[10:11]
	s_mov_b32 m0, s65
	s_nop 0
	global_load_lds_dwordx4 v[190:191], off
	v_lshl_add_u64 v[190:191], v[226:227], 0, s[10:11]
	s_mov_b32 m0, s66
	s_nop 0
	global_load_lds_dwordx4 v[190:191], off
	s_waitcnt vmcnt(8)
	s_waitcnt lgkmcnt(0)
	s_barrier
	s_setprio 1
	s_waitcnt lgkmcnt(0)
	v_mfma_f32_16x16x32_bf16 v[60:63], v[150:153], v[182:185], v[60:63]
	v_mfma_f32_16x16x32_bf16 v[56:59], v[158:161], v[182:185], v[56:59]
	v_mfma_f32_16x16x32_bf16 v[52:55], v[150:153], v[196:199], v[52:55]
	v_mfma_f32_16x16x32_bf16 v[48:51], v[158:161], v[196:199], v[48:51]
	v_mfma_f32_16x16x32_bf16 v[36:39], v[150:153], v[208:211], v[36:39]
	v_mfma_f32_16x16x32_bf16 v[32:35], v[158:161], v[208:211], v[32:35]
	v_mfma_f32_16x16x32_bf16 v[20:23], v[150:153], v[216:219], v[20:23]
	v_mfma_f32_16x16x32_bf16 v[16:19], v[158:161], v[216:219], v[16:19]
	v_mfma_f32_16x16x32_bf16 v[60:63], v[154:157], v[186:189], v[60:63]
	v_mfma_f32_16x16x32_bf16 v[56:59], v[162:165], v[186:189], v[56:59]
	v_mfma_f32_16x16x32_bf16 v[52:55], v[154:157], v[200:203], v[52:55]
	v_mfma_f32_16x16x32_bf16 v[48:51], v[162:165], v[200:203], v[48:51]
	v_mfma_f32_16x16x32_bf16 v[36:39], v[154:157], v[212:215], v[36:39]
	v_mfma_f32_16x16x32_bf16 v[32:35], v[162:165], v[212:215], v[32:35]
	v_mfma_f32_16x16x32_bf16 v[20:23], v[154:157], v[220:223], v[20:23]
	v_mfma_f32_16x16x32_bf16 v[16:19], v[162:165], v[220:223], v[16:19]
	s_setprio 0
	s_setprio 1
	v_mfma_f32_16x16x32_bf16 v[44:47], v[166:169], v[182:185], v[44:47]
	v_mfma_f32_16x16x32_bf16 v[40:43], v[174:177], v[182:185], v[40:43]
	v_mfma_f32_16x16x32_bf16 v[28:31], v[166:169], v[196:199], v[28:31]
	v_mfma_f32_16x16x32_bf16 v[24:27], v[174:177], v[196:199], v[24:27]
	v_mfma_f32_16x16x32_bf16 v[12:15], v[166:169], v[208:211], v[12:15]
	v_mfma_f32_16x16x32_bf16 v[8:11], v[174:177], v[208:211], v[8:11]
	v_mfma_f32_16x16x32_bf16 v[4:7], v[166:169], v[216:219], v[4:7]
	v_mfma_f32_16x16x32_bf16 v[0:3], v[174:177], v[216:219], v[0:3]
	v_mfma_f32_16x16x32_bf16 v[44:47], v[170:173], v[186:189], v[44:47]
	v_mfma_f32_16x16x32_bf16 v[40:43], v[178:181], v[186:189], v[40:43]
	v_mfma_f32_16x16x32_bf16 v[28:31], v[170:173], v[200:203], v[28:31]
	v_mfma_f32_16x16x32_bf16 v[24:27], v[178:181], v[200:203], v[24:27]
	v_mfma_f32_16x16x32_bf16 v[12:15], v[170:173], v[212:215], v[12:15]
	v_mfma_f32_16x16x32_bf16 v[8:11], v[178:181], v[212:215], v[8:11]
	v_mfma_f32_16x16x32_bf16 v[4:7], v[170:173], v[220:223], v[4:7]
	v_mfma_f32_16x16x32_bf16 v[0:3], v[178:181], v[220:223], v[0:3]
	s_setprio 0
	s_add_i32 s79, s79, 2
	s_add_u32 s54, s54, 0x100
	s_addc_u32 s55, s55, 0
	s_add_u32 s77, s77, 0x100
	s_addc_u32 s78, s78, 0
	s_cmp_gt_u32 s79, 29
	s_barrier
	s_cbranch_scc0 .LBB0_141
	s_and_b64 vcc, exec, s[18:19]
	s_cbranch_vccz .LBB0_144
	s_barrier

; #define PG8_STAGE(bufoff, gbase, voff) do { _Pragma("unroll") for (int _i = 0; _i < 2; ++_i) \
;         __builtin_amdgcn_global_load_lds((const unsigned*)((const char*)(gbase) + (voff)[_i]), (LAS unsigned*)(lds + (bufoff) + ldsw + _i * 8192), 16, 0, 0); } while (0)
; #define PG8_LDA(dst, b, h) do { _Pragma("unroll") for (int m = 0; m < 4; ++m) _Pragma("unroll") for (int k = 0; k < 2; ++k) dst[m][k] = *(const LAS bf16x8*)(lds + PG8_SA(b, h) + aoff + m * 2048 + k * 1024); } while (0)
; #define PG8_LDB(dst, b, h) do { _Pragma("unroll") for (int n = 0; n < 2; ++n) _Pragma("unroll") for (int k = 0; k < 2; ++k) dst[n][k] = *(const LAS bf16x8*)(lds + PG8_SB(b, h) + boff + n * 2048 + k * 1024); } while (0)
; #define PG8_MMA(ai, bj, At, Bt) do { __builtin_amdgcn_s_setprio(1); _Pragma("unroll") for (int m = 0; m < 4; ++m) _Pragma("unroll") for (int n = 0; n < 2; ++n) _Pragma("unroll") for (int k = 0; k < 2; ++k) \
;         acc[ai][bj][m][n] = __builtin_amdgcn_mfma_f32_16x16x32_bf16(Bt[n][k], At[m][k], acc[ai][bj][m][n], 0, 0, 0); __builtin_amdgcn_s_setprio(0); } while (0)
; #define PG8_WAIT_V(n) asm volatile("s_waitcnt vmcnt(" #n ")" ::: "memory")
; #define PG8_WAIT_L(n) asm volatile("s_waitcnt lgkmcnt(" #n ")" ::: "memory")
; #define PG8_BAR __builtin_amdgcn_s_barrier()
; #define PG8_SCHED __builtin_amdgcn_sched_barrier(0)
; template <class Epi, class Sched>
; __device__ __forceinline__ void gemm_phase(LAS unsigned char* lds, const Gemm g, const Sched& S, const Epi& E) {
;     ...
;             PG8_LDB(B0, 0, 0); PG8_LDB(B1, 0, 1); PG8_SCHED; PG8_LDA(At, 0, 0); PG8_STAGE(PG8_SA(1, 1), a1 + hstepA, voffA);
;             PG8_WAIT_V(8); PG8_WAIT_L(0); PG8_BAR; PG8_MMA(0, 0, At, B0); PG8_MMA(0, 1, At, B1); PG8_BAR; PG8_SCHED;
;             PG8_LDA(At, 0, 1); PG8_STAGE(PG8_SB(0, 0), b2, voffB); PG8_STAGE(PG8_SB(0, 1), b2 + hstepB, voffB); PG8_STAGE(PG8_SA(0, 0), a2, voffA);
;             PG8_WAIT_V(8); PG8_WAIT_L(0); PG8_BAR; PG8_MMA(1, 0, At, B0); PG8_MMA(1, 1, At, B1); PG8_BAR; PG8_SCHED;
.LBB0_518:
	ds_read_b128 v[140:143], v151
	ds_read_b128 v[156:159], v151 offset:1024
	ds_read_b128 v[160:163], v151 offset:2048
	ds_read_b128 v[164:167], v151 offset:3072
	ds_read_b128 v[168:171], v152
	ds_read_b128 v[172:175], v152 offset:1024
	ds_read_b128 v[176:179], v152 offset:2048
	ds_read_b128 v[180:183], v152 offset:3072
	s_add_u32 s16, s54, 0xfff80080
	s_addc_u32 s17, s55, -1
	s_cmp_eq_u32 s75, 28
	s_cselect_b32 s59, s15, s17
	s_cselect_b32 s58, s47, s16
	s_cselect_b32 s57, s45, s74
	s_cselect_b32 s56, s53, s73
	v_lshl_add_u64 v[144:145], s[54:55], 0, v[132:133]
	s_add_i32 m0, s62, 0xc000
	ds_read_b128 v[184:187], v153
	ds_read_b128 v[188:191], v153 offset:1024
	ds_read_b128 v[198:201], v153 offset:2048
	ds_read_b128 v[202:205], v153 offset:3072
	ds_read_b128 v[210:213], v153 offset:4096
	ds_read_b128 v[214:217], v153 offset:5120
	ds_read_b128 v[218:221], v153 offset:6144
	ds_read_b128 v[222:225], v153 offset:7168
	global_load_lds_dwordx4 v[144:145], off
	v_lshl_add_u64 v[144:145], s[54:55], 0, v[134:135]
	s_add_i32 m0, s62, 0xe000
	s_nop 0
	global_load_lds_dwordx4 v[144:145], off
	s_waitcnt vmcnt(8)
	s_waitcnt lgkmcnt(0)
	s_barrier
	s_setprio 1
	s_waitcnt lgkmcnt(0)
	v_mfma_f32_16x16x32_bf16 v[124:127], v[140:143], v[184:187], v[124:127]
	v_mfma_f32_16x16x32_bf16 v[120:123], v[160:163], v[184:187], v[120:123]
	v_mfma_f32_16x16x32_bf16 v[108:111], v[140:143], v[198:201], v[108:111]
	v_mfma_f32_16x16x32_bf16 v[104:107], v[160:163], v[198:201], v[104:107]
	v_mfma_f32_16x16x32_bf16 v[92:95], v[140:143], v[210:213], v[92:95]
	v_mfma_f32_16x16x32_bf16 v[88:91], v[160:163], v[210:213], v[88:91]
	v_mfma_f32_16x16x32_bf16 v[76:79], v[140:143], v[218:221], v[76:79]
	v_mfma_f32_16x16x32_bf16 v[72:75], v[160:163], v[218:221], v[72:75]
	v_mfma_f32_16x16x32_bf16 v[124:127], v[156:159], v[188:191], v[124:127]
	v_mfma_f32_16x16x32_bf16 v[120:123], v[164:167], v[188:191], v[120:123]
	v_mfma_f32_16x16x32_bf16 v[108:111], v[156:159], v[202:205], v[108:111]
	v_mfma_f32_16x16x32_bf16 v[104:107], v[164:167], v[202:205], v[104:107]
	v_mfma_f32_16x16x32_bf16 v[92:95], v[156:159], v[214:217], v[92:95]
	v_mfma_f32_16x16x32_bf16 v[88:91], v[164:167], v[214:217], v[88:91]
	v_mfma_f32_16x16x32_bf16 v[76:79], v[156:159], v[222:225], v[76:79]
	v_mfma_f32_16x16x32_bf16 v[72:75], v[164:167], v[222:225], v[72:75]
	s_setprio 0
	s_setprio 1
	v_mfma_f32_16x16x32_bf16 v[116:119], v[168:171], v[184:187], v[116:119]
	v_mfma_f32_16x16x32_bf16 v[112:115], v[176:179], v[184:187], v[112:115]
	v_mfma_f32_16x16x32_bf16 v[100:103], v[168:171], v[198:201], v[100:103]
	v_mfma_f32_16x16x32_bf16 v[96:99], v[176:179], v[198:201], v[96:99]
	v_mfma_f32_16x16x32_bf16 v[84:87], v[168:171], v[210:213], v[84:87]
	v_mfma_f32_16x16x32_bf16 v[80:83], v[176:179], v[210:213], v[80:83]
	v_mfma_f32_16x16x32_bf16 v[68:71], v[168:171], v[218:221], v[68:71]
	v_mfma_f32_16x16x32_bf16 v[64:67], v[176:179], v[218:221], v[64:67]
	v_mfma_f32_16x16x32_bf16 v[116:119], v[172:175], v[188:191], v[116:119]
	v_mfma_f32_16x16x32_bf16 v[112:115], v[180:183], v[188:191], v[112:115]
	v_mfma_f32_16x16x32_bf16 v[100:103], v[172:175], v[202:205], v[100:103]
	v_mfma_f32_16x16x32_bf16 v[96:99], v[180:183], v[202:205], v[96:99]
	v_mfma_f32_16x16x32_bf16 v[84:87], v[172:175], v[214:217], v[84:87]
	v_mfma_f32_16x16x32_bf16 v[80:83], v[180:183], v[214:217], v[80:83]
	v_mfma_f32_16x16x32_bf16 v[68:71], v[172:175], v[222:225], v[68:71]
	v_mfma_f32_16x16x32_bf16 v[64:67], v[180:183], v[222:225], v[64:67]
	s_setprio 0
	s_barrier
	s_add_i32 s16, s71, s61
	v_lshl_add_u64 v[144:145], s[56:57], 0, v[128:129]
	s_mov_b32 m0, s16
	ds_read_b128 v[184:187], v153 offset:16384
	ds_read_b128 v[188:191], v153 offset:17408
	ds_read_b128 v[198:201], v153 offset:18432
	ds_read_b128 v[202:205], v153 offset:19456
	ds_read_b128 v[210:213], v153 offset:20480
	ds_read_b128 v[214:217], v153 offset:21504
	ds_read_b128 v[218:221], v153 offset:22528
	ds_read_b128 v[222:225], v153 offset:23552
	global_load_lds_dwordx4 v[144:145], off
	s_add_i32 m0, s16, 0x2000
	s_add_u32 s34, s56, 0x80000
	v_lshl_add_u64 v[226:227], s[56:57], 0, v[130:131]
	s_addc_u32 s35, s57, 0
	s_add_i32 s16, s72, s61
	global_load_lds_dwordx4 v[226:227], off
	v_lshl_add_u64 v[228:229], s[34:35], 0, v[128:129]
	s_mov_b32 m0, s16
	v_lshl_add_u64 v[230:231], s[58:59], 0, v[130:131]
	global_load_lds_dwordx4 v[228:229], off
	v_lshl_add_u64 v[228:229], s[34:35], 0, v[130:131]
	s_add_i32 m0, s16, 0x2000
	s_nop 0
	global_load_lds_dwordx4 v[228:229], off
	v_lshl_add_u64 v[228:229], s[58:59], 0, v[128:129]
	s_mov_b32 m0, s62
	s_nop 0
	global_load_lds_dwordx4 v[228:229], off
	s_mov_b32 m0, s63
	s_nop 0
	global_load_lds_dwordx4 v[230:231], off
	s_waitcnt vmcnt(8)
	s_waitcnt lgkmcnt(0)
	s_barrier
; #define PG8_STAGE(bufoff, gbase, voff) do { _Pragma("unroll") for (int _i = 0; _i < 2; ++_i) \
;         __builtin_amdgcn_global_load_lds((const unsigned*)((const char*)(gbase) + (voff)[_i]), (LAS unsigned*)(lds + (bufoff) + ldsw + _i * 8192), 16, 0, 0); } while (0)
; #define PG8_LDA(dst, b, h) do { _Pragma("unroll") for (int m = 0; m < 4; ++m) _Pragma("unroll") for (int k = 0; k < 2; ++k) dst[m][k] = *(const LAS bf16x8*)(lds + PG8_SA(b, h) + aoff + m * 2048 + k * 1024); } while (0)
; #define PG8_LDB(dst, b, h) do { _Pragma("unroll") for (int n = 0; n < 2; ++n) _Pragma("unroll") for (int k = 0; k < 2; ++k) dst[n][k] = *(const LAS bf16x8*)(lds + PG8_SB(b, h) + boff + n * 2048 + k * 1024); } while (0)
; #define PG8_MMA(ai, bj, At, Bt) do { __builtin_amdgcn_s_setprio(1); _Pragma("unroll") for (int m = 0; m < 4; ++m) _Pragma("unroll") for (int n = 0; n < 2; ++n) _Pragma("unroll") for (int k = 0; k < 2; ++k) \
;         acc[ai][bj][m][n] = __builtin_amdgcn_mfma_f32_16x16x32_bf16(Bt[n][k], At[m][k], acc[ai][bj][m][n], 0, 0, 0); __builtin_amdgcn_s_setprio(0); } while (0)
; #define PG8_WAIT_V(n) asm volatile("s_waitcnt vmcnt(" #n ")" ::: "memory")
; #define PG8_WAIT_L(n) asm volatile("s_waitcnt lgkmcnt(" #n ")" ::: "memory")
; #define PG8_BAR __builtin_amdgcn_s_barrier()
; #define PG8_SCHED __builtin_amdgcn_sched_barrier(0)
; template <class Epi, class Sched>
; __device__ __forceinline__ void gemm_phase(LAS unsigned char* lds, const Gemm g, const Sched& S, const Epi& E) {
;     ...
;             PG8_WAIT_V(8); PG8_WAIT_L(0); PG8_BAR; PG8_MMA(1, 0, At, B0); PG8_MMA(1, 1, At, B1); PG8_BAR; PG8_SCHED;
;             PG8_LDB(B0, 1, 0); PG8_LDB(B1, 1, 1); PG8_SCHED; PG8_LDA(At, 1, 0); PG8_STAGE(PG8_SA(0, 1), a2 + hstepA, voffA);
;             PG8_WAIT_V(8); PG8_WAIT_L(0); PG8_BAR; PG8_MMA(0, 0, At, B0); PG8_MMA(0, 1, At, B1); PG8_BAR; PG8_SCHED;
;             PG8_LDA(At, 1, 1); PG8_STAGE(PG8_SB(1, 0), b3, voffB); PG8_STAGE(PG8_SB(1, 1), b3 + hstepB, voffB); PG8_STAGE(PG8_SA(1, 0), a3, voffA);
	s_setprio 1
	s_waitcnt lgkmcnt(0)
	v_mfma_f32_16x16x32_bf16 v[60:63], v[140:143], v[184:187], v[60:63]
	v_mfma_f32_16x16x32_bf16 v[56:59], v[160:163], v[184:187], v[56:59]
	v_mfma_f32_16x16x32_bf16 v[44:47], v[140:143], v[198:201], v[44:47]
	v_mfma_f32_16x16x32_bf16 v[40:43], v[160:163], v[198:201], v[40:43]
	v_mfma_f32_16x16x32_bf16 v[28:31], v[140:143], v[210:213], v[28:31]
	v_mfma_f32_16x16x32_bf16 v[24:27], v[160:163], v[210:213], v[24:27]
	v_mfma_f32_16x16x32_bf16 v[12:15], v[140:143], v[218:221], v[12:15]
	v_mfma_f32_16x16x32_bf16 v[8:11], v[160:163], v[218:221], v[8:11]
	v_mfma_f32_16x16x32_bf16 v[60:63], v[156:159], v[188:191], v[60:63]
	v_mfma_f32_16x16x32_bf16 v[56:59], v[164:167], v[188:191], v[56:59]
	v_mfma_f32_16x16x32_bf16 v[44:47], v[156:159], v[202:205], v[44:47]
	v_mfma_f32_16x16x32_bf16 v[40:43], v[164:167], v[202:205], v[40:43]
	v_mfma_f32_16x16x32_bf16 v[28:31], v[156:159], v[214:217], v[28:31]
	v_mfma_f32_16x16x32_bf16 v[24:27], v[164:167], v[214:217], v[24:27]
	v_mfma_f32_16x16x32_bf16 v[12:15], v[156:159], v[222:225], v[12:15]
	v_mfma_f32_16x16x32_bf16 v[8:11], v[164:167], v[222:225], v[8:11]
	s_setprio 0
	s_setprio 1
	v_mfma_f32_16x16x32_bf16 v[52:55], v[168:171], v[184:187], v[52:55]
	v_mfma_f32_16x16x32_bf16 v[48:51], v[176:179], v[184:187], v[48:51]
	v_mfma_f32_16x16x32_bf16 v[36:39], v[168:171], v[198:201], v[36:39]
	v_mfma_f32_16x16x32_bf16 v[32:35], v[176:179], v[198:201], v[32:35]
	v_mfma_f32_16x16x32_bf16 v[20:23], v[168:171], v[210:213], v[20:23]
	v_mfma_f32_16x16x32_bf16 v[16:19], v[176:179], v[210:213], v[16:19]
	v_mfma_f32_16x16x32_bf16 v[4:7], v[168:171], v[218:221], v[4:7]
	v_mfma_f32_16x16x32_bf16 v[0:3], v[176:179], v[218:221], v[0:3]
	v_mfma_f32_16x16x32_bf16 v[52:55], v[172:175], v[188:191], v[52:55]
	v_mfma_f32_16x16x32_bf16 v[48:51], v[180:183], v[188:191], v[48:51]
	v_mfma_f32_16x16x32_bf16 v[36:39], v[172:175], v[202:205], v[36:39]
	v_mfma_f32_16x16x32_bf16 v[32:35], v[180:183], v[202:205], v[32:35]
	v_mfma_f32_16x16x32_bf16 v[20:23], v[172:175], v[214:217], v[20:23]
	v_mfma_f32_16x16x32_bf16 v[16:19], v[180:183], v[214:217], v[16:19]
	v_mfma_f32_16x16x32_bf16 v[4:7], v[172:175], v[222:225], v[4:7]
	v_mfma_f32_16x16x32_bf16 v[0:3], v[180:183], v[222:225], v[0:3]
	s_setprio 0
	s_barrier
	s_add_i32 s16, 0, 0x18000
	v_add_u32_e32 v155, s16, v147
	s_add_i32 s17, 0, 0x1c000
	ds_read_b128 v[140:143], v155
	ds_read_b128 v[156:159], v155 offset:1024
	ds_read_b128 v[160:163], v155 offset:2048
	ds_read_b128 v[164:167], v155 offset:3072
	v_add_u32_e32 v155, s17, v147
	ds_read_b128 v[168:171], v155
	ds_read_b128 v[172:175], v155 offset:1024
	ds_read_b128 v[176:179], v155 offset:2048
	ds_read_b128 v[180:183], v155 offset:3072
	s_add_u32 s34, s58, 0x80000
	s_addc_u32 s35, s59, 0
	s_mov_b32 m0, s64
	v_lshl_add_u64 v[232:233], s[34:35], 0, v[128:129]
	ds_read_b128 v[184:187], v153 offset:32768
	ds_read_b128 v[188:191], v153 offset:33792
	ds_read_b128 v[198:201], v153 offset:34816
	ds_read_b128 v[202:205], v153 offset:35840
	ds_read_b128 v[210:213], v153 offset:36864
	ds_read_b128 v[214:217], v153 offset:37888
	ds_read_b128 v[218:221], v153 offset:38912
	ds_read_b128 v[222:225], v153 offset:39936
	global_load_lds_dwordx4 v[232:233], off
	v_lshl_add_u64 v[232:233], s[34:35], 0, v[130:131]
	s_mov_b32 m0, s65
	s_nop 0
	global_load_lds_dwordx4 v[232:233], off
	s_waitcnt vmcnt(8)
	s_waitcnt lgkmcnt(0)
	s_barrier
	s_setprio 1
	s_waitcnt lgkmcnt(0)
	v_mfma_f32_16x16x32_bf16 v[124:127], v[140:143], v[184:187], v[124:127]
	v_mfma_f32_16x16x32_bf16 v[120:123], v[160:163], v[184:187], v[120:123]
	v_mfma_f32_16x16x32_bf16 v[108:111], v[140:143], v[198:201], v[108:111]
	v_mfma_f32_16x16x32_bf16 v[104:107], v[160:163], v[198:201], v[104:107]
	v_mfma_f32_16x16x32_bf16 v[92:95], v[140:143], v[210:213], v[92:95]
	v_mfma_f32_16x16x32_bf16 v[88:91], v[160:163], v[210:213], v[88:91]
	v_mfma_f32_16x16x32_bf16 v[76:79], v[140:143], v[218:221], v[76:79]
	v_mfma_f32_16x16x32_bf16 v[72:75], v[160:163], v[218:221], v[72:75]
	v_mfma_f32_16x16x32_bf16 v[124:127], v[156:159], v[188:191], v[124:127]
	v_mfma_f32_16x16x32_bf16 v[120:123], v[164:167], v[188:191], v[120:123]
	v_mfma_f32_16x16x32_bf16 v[108:111], v[156:159], v[202:205], v[108:111]
	v_mfma_f32_16x16x32_bf16 v[104:107], v[164:167], v[202:205], v[104:107]
	v_mfma_f32_16x16x32_bf16 v[92:95], v[156:159], v[214:217], v[92:95]
	v_mfma_f32_16x16x32_bf16 v[88:91], v[164:167], v[214:217], v[88:91]
	v_mfma_f32_16x16x32_bf16 v[76:79], v[156:159], v[222:225], v[76:79]
	v_mfma_f32_16x16x32_bf16 v[72:75], v[164:167], v[222:225], v[72:75]
	s_setprio 0
	s_setprio 1
	v_mfma_f32_16x16x32_bf16 v[116:119], v[168:171], v[184:187], v[116:119]
	v_mfma_f32_16x16x32_bf16 v[112:115], v[176:179], v[184:187], v[112:115]
	v_mfma_f32_16x16x32_bf16 v[100:103], v[168:171], v[198:201], v[100:103]
	v_mfma_f32_16x16x32_bf16 v[96:99], v[176:179], v[198:201], v[96:99]
	v_mfma_f32_16x16x32_bf16 v[84:87], v[168:171], v[210:213], v[84:87]
	v_mfma_f32_16x16x32_bf16 v[80:83], v[176:179], v[210:213], v[80:83]
	v_mfma_f32_16x16x32_bf16 v[68:71], v[168:171], v[218:221], v[68:71]
	v_mfma_f32_16x16x32_bf16 v[64:67], v[176:179], v[218:221], v[64:67]
	v_mfma_f32_16x16x32_bf16 v[116:119], v[172:175], v[188:191], v[116:119]
	v_mfma_f32_16x16x32_bf16 v[112:115], v[180:183], v[188:191], v[112:115]
	v_mfma_f32_16x16x32_bf16 v[100:103], v[172:175], v[202:205], v[100:103]
	v_mfma_f32_16x16x32_bf16 v[96:99], v[180:183], v[202:205], v[96:99]
	v_mfma_f32_16x16x32_bf16 v[84:87], v[172:175], v[214:217], v[84:87]
	v_mfma_f32_16x16x32_bf16 v[80:83], v[180:183], v[214:217], v[80:83]
	v_mfma_f32_16x16x32_bf16 v[68:71], v[172:175], v[222:225], v[68:71]
	v_mfma_f32_16x16x32_bf16 v[64:67], v[180:183], v[222:225], v[64:67]
	s_setprio 0
	s_barrier
; #define PG8_STAGE(bufoff, gbase, voff) do { _Pragma("unroll") for (int _i = 0; _i < 2; ++_i) \
;         __builtin_amdgcn_global_load_lds((const unsigned*)((const char*)(gbase) + (voff)[_i]), (LAS unsigned*)(lds + (bufoff) + ldsw + _i * 8192), 16, 0, 0); } while (0)
; #define PG8_LDA(dst, b, h) do { _Pragma("unroll") for (int m = 0; m < 4; ++m) _Pragma("unroll") for (int k = 0; k < 2; ++k) dst[m][k] = *(const LAS bf16x8*)(lds + PG8_SA(b, h) + aoff + m * 2048 + k * 1024); } while (0)
; #define PG8_LDB(dst, b, h) do { _Pragma("unroll") for (int n = 0; n < 2; ++n) _Pragma("unroll") for (int k = 0; k < 2; ++k) dst[n][k] = *(const LAS bf16x8*)(lds + PG8_SB(b, h) + boff + n * 2048 + k * 1024); } while (0)
; #define PG8_WAIT_V(n) asm volatile("s_waitcnt vmcnt(" #n ")" ::: "memory")
; #define PG8_BAR __builtin_amdgcn_s_barrier()
; template <class Epi, class Sched>
; __device__ __forceinline__ void gemm_phase(LAS unsigned char* lds, const Gemm g, const Sched& S, const Epi& E) {
;     ...
;         for (int t = 0; t < nt; t += 2) {
;             const bool last = (t == nt - 2);
;             const char* a1 = cA + (size_t)(t + 1) * kstep;
;             const char* a2 = last ? nA : cA + (size_t)(t + 2) * kstep; const char* b2 = last ? nB : cB + (size_t)(t + 2) * kstep;
;             const char* a3 = a2 + kstep; const char* b3 = b2 + kstep;
;             PG8_LDB(B0, 0, 0); PG8_LDB(B1, 0, 1); PG8_SCHED; PG8_LDA(At, 0, 0); PG8_STAGE(PG8_SA(1, 1), a1 + hstepA, voffA);
;             PG8_WAIT_V(8); PG8_WAIT_L(0); PG8_BAR; PG8_MMA(0, 0, At, B0); PG8_MMA(0, 1, At, B1); PG8_BAR; PG8_SCHED;
;             PG8_LDA(At, 0, 1); PG8_STAGE(PG8_SB(0, 0), b2, voffB); PG8_STAGE(PG8_SB(0, 1), b2 + hstepB, voffB); PG8_STAGE(PG8_SA(0, 0), a2, voffA);
;             PG8_WAIT_V(8); PG8_WAIT_L(0); PG8_BAR; PG8_MMA(1, 0, At, B0); PG8_MMA(1, 1, At, B1); PG8_BAR; PG8_SCHED;
;             PG8_LDB(B0, 1, 0); PG8_LDB(B1, 1, 1); PG8_SCHED; PG8_LDA(At, 1, 0); PG8_STAGE(PG8_SA(0, 1), a2 + hstepA, voffA);
;             PG8_WAIT_V(8); PG8_WAIT_L(0); PG8_BAR; PG8_MMA(0, 0, At, B0); PG8_MMA(0, 1, At, B1); PG8_BAR; PG8_SCHED;
;             PG8_LDA(At, 1, 1); PG8_STAGE(PG8_SB(1, 0), b3, voffB); PG8_STAGE(PG8_SB(1, 1), b3 + hstepB, voffB); PG8_STAGE(PG8_SA(1, 0), a3, voffA);
;             PG8_WAIT_V(8); PG8_WAIT_L(0); PG8_BAR; PG8_MMA(1, 0, At, B0); PG8_MMA(1, 1, At, B1); PG8_BAR; PG8_SCHED;
	s_add_i32 s16, s16, s61
	v_lshl_add_u64 v[144:145], v[144:145], 0, s[28:29]
	s_mov_b32 m0, s16
	ds_read_b128 v[184:187], v153 offset:49152
	ds_read_b128 v[188:191], v153 offset:50176
	ds_read_b128 v[198:201], v153 offset:51200
	ds_read_b128 v[202:205], v153 offset:52224
	ds_read_b128 v[210:213], v153 offset:53248
	ds_read_b128 v[214:217], v153 offset:54272
	ds_read_b128 v[218:221], v153 offset:55296
	ds_read_b128 v[222:225], v153 offset:56320
	global_load_lds_dwordx4 v[144:145], off
	s_add_i32 m0, s16, 0x2000
	s_add_u32 s34, s56, 0x80080
	v_lshl_add_u64 v[144:145], v[226:227], 0, s[28:29]
	s_addc_u32 s35, s57, 0
	s_add_i32 s16, s17, s61
	global_load_lds_dwordx4 v[144:145], off
	v_lshl_add_u64 v[144:145], s[34:35], 0, v[128:129]
	s_mov_b32 m0, s16
	s_nop 0
	global_load_lds_dwordx4 v[144:145], off
	v_lshl_add_u64 v[144:145], s[34:35], 0, v[130:131]
	s_add_i32 m0, s16, 0x2000
	s_nop 0
	global_load_lds_dwordx4 v[144:145], off
	v_lshl_add_u64 v[144:145], v[228:229], 0, s[28:29]
	s_mov_b32 m0, s67
	s_nop 0
	global_load_lds_dwordx4 v[144:145], off
	v_lshl_add_u64 v[144:145], v[230:231], 0, s[28:29]
	s_mov_b32 m0, s68
	s_nop 0
	global_load_lds_dwordx4 v[144:145], off
	s_waitcnt vmcnt(8)
	s_waitcnt lgkmcnt(0)
	s_barrier
	s_setprio 1
	s_waitcnt lgkmcnt(0)
	v_mfma_f32_16x16x32_bf16 v[60:63], v[140:143], v[184:187], v[60:63]
	v_mfma_f32_16x16x32_bf16 v[56:59], v[160:163], v[184:187], v[56:59]
	v_mfma_f32_16x16x32_bf16 v[44:47], v[140:143], v[198:201], v[44:47]
	v_mfma_f32_16x16x32_bf16 v[40:43], v[160:163], v[198:201], v[40:43]
	v_mfma_f32_16x16x32_bf16 v[28:31], v[140:143], v[210:213], v[28:31]
	v_mfma_f32_16x16x32_bf16 v[24:27], v[160:163], v[210:213], v[24:27]
	v_mfma_f32_16x16x32_bf16 v[12:15], v[140:143], v[218:221], v[12:15]
	v_mfma_f32_16x16x32_bf16 v[8:11], v[160:163], v[218:221], v[8:11]
	v_mfma_f32_16x16x32_bf16 v[60:63], v[156:159], v[188:191], v[60:63]
	v_mfma_f32_16x16x32_bf16 v[56:59], v[164:167], v[188:191], v[56:59]
	v_mfma_f32_16x16x32_bf16 v[44:47], v[156:159], v[202:205], v[44:47]
	v_mfma_f32_16x16x32_bf16 v[40:43], v[164:167], v[202:205], v[40:43]
	v_mfma_f32_16x16x32_bf16 v[28:31], v[156:159], v[214:217], v[28:31]
	v_mfma_f32_16x16x32_bf16 v[24:27], v[164:167], v[214:217], v[24:27]
	v_mfma_f32_16x16x32_bf16 v[12:15], v[156:159], v[222:225], v[12:15]
	v_mfma_f32_16x16x32_bf16 v[8:11], v[164:167], v[222:225], v[8:11]
	s_setprio 0
	s_setprio 1
	v_mfma_f32_16x16x32_bf16 v[52:55], v[168:171], v[184:187], v[52:55]
	v_mfma_f32_16x16x32_bf16 v[48:51], v[176:179], v[184:187], v[48:51]
	v_mfma_f32_16x16x32_bf16 v[36:39], v[168:171], v[198:201], v[36:39]
	v_mfma_f32_16x16x32_bf16 v[32:35], v[176:179], v[198:201], v[32:35]
	v_mfma_f32_16x16x32_bf16 v[20:23], v[168:171], v[210:213], v[20:23]
	v_mfma_f32_16x16x32_bf16 v[16:19], v[176:179], v[210:213], v[16:19]
	v_mfma_f32_16x16x32_bf16 v[4:7], v[168:171], v[218:221], v[4:7]
	v_mfma_f32_16x16x32_bf16 v[0:3], v[176:179], v[218:221], v[0:3]
	v_mfma_f32_16x16x32_bf16 v[52:55], v[172:175], v[188:191], v[52:55]
	v_mfma_f32_16x16x32_bf16 v[48:51], v[180:183], v[188:191], v[48:51]
	v_mfma_f32_16x16x32_bf16 v[36:39], v[172:175], v[202:205], v[36:39]
	v_mfma_f32_16x16x32_bf16 v[32:35], v[180:183], v[202:205], v[32:35]
	v_mfma_f32_16x16x32_bf16 v[20:23], v[172:175], v[214:217], v[20:23]
	v_mfma_f32_16x16x32_bf16 v[16:19], v[180:183], v[214:217], v[16:19]
	v_mfma_f32_16x16x32_bf16 v[4:7], v[172:175], v[222:225], v[4:7]
	v_mfma_f32_16x16x32_bf16 v[0:3], v[180:183], v[222:225], v[0:3]
	s_setprio 0
	s_add_i32 s75, s75, 2
	s_add_u32 s54, s54, 0x100
	s_addc_u32 s55, s55, 0
	s_add_u32 s73, s73, 0x100
	s_addc_u32 s74, s74, 0
	s_cmp_gt_u32 s75, 29
	s_barrier
	s_cbranch_scc0 .LBB0_518
	s_and_b64 vcc, exec, s[30:31]
	s_cbranch_vccz .LBB0_521
	s_barrier

; #define PG8_STAGE(bufoff, gbase, voff) do { _Pragma("unroll") for (int _i = 0; _i < 2; ++_i) \
;         __builtin_amdgcn_global_load_lds((const unsigned*)((const char*)(gbase) + (voff)[_i]), (LAS unsigned*)(lds + (bufoff) + ldsw + _i * 8192), 16, 0, 0); } while (0)
; #define PG8_LDA(dst, b, h) do { _Pragma("unroll") for (int m = 0; m < 4; ++m) _Pragma("unroll") for (int k = 0; k < 2; ++k) dst[m][k] = *(const LAS bf16x8*)(lds + PG8_SA(b, h) + aoff + m * 2048 + k * 1024); } while (0)
; #define PG8_LDB(dst, b, h) do { _Pragma("unroll") for (int n = 0; n < 2; ++n) _Pragma("unroll") for (int k = 0; k < 2; ++k) dst[n][k] = *(const LAS bf16x8*)(lds + PG8_SB(b, h) + boff + n * 2048 + k * 1024); } while (0)
; #define PG8_MMA(ai, bj, At, Bt) do { __builtin_amdgcn_s_setprio(1); _Pragma("unroll") for (int m = 0; m < 4; ++m) _Pragma("unroll") for (int n = 0; n < 2; ++n) _Pragma("unroll") for (int k = 0; k < 2; ++k) \
;         acc[ai][bj][m][n] = __builtin_amdgcn_mfma_f32_16x16x32_bf16(Bt[n][k], At[m][k], acc[ai][bj][m][n], 0, 0, 0); __builtin_amdgcn_s_setprio(0); } while (0)
; #define PG8_WAIT_V(n) asm volatile("s_waitcnt vmcnt(" #n ")" ::: "memory")
; #define PG8_WAIT_L(n) asm volatile("s_waitcnt lgkmcnt(" #n ")" ::: "memory")
; #define PG8_BAR __builtin_amdgcn_s_barrier()
; #define PG8_SCHED __builtin_amdgcn_sched_barrier(0)
; template <class Epi, class Sched>
; __device__ __forceinline__ void gemm_phase(LAS unsigned char* lds, const Gemm g, const Sched& S, const Epi& E) {
;     ...
;             PG8_LDB(B0, 0, 0); PG8_LDB(B1, 0, 1); PG8_SCHED; PG8_LDA(At, 0, 0); PG8_STAGE(PG8_SA(1, 1), a1 + hstepA, voffA);
;             PG8_WAIT_V(8); PG8_WAIT_L(0); PG8_BAR; PG8_MMA(0, 0, At, B0); PG8_MMA(0, 1, At, B1); PG8_BAR; PG8_SCHED;
;             PG8_LDA(At, 0, 1); PG8_STAGE(PG8_SB(0, 0), b2, voffB); PG8_STAGE(PG8_SB(0, 1), b2 + hstepB, voffB); PG8_STAGE(PG8_SA(0, 0), a2, voffA);
;             PG8_WAIT_V(8); PG8_WAIT_L(0); PG8_BAR; PG8_MMA(1, 0, At, B0); PG8_MMA(1, 1, At, B1); PG8_BAR; PG8_SCHED;
.LBB0_633:
	ds_read_b128 v[150:153], v147
	ds_read_b128 v[154:157], v147 offset:1024
	ds_read_b128 v[158:161], v147 offset:2048
	ds_read_b128 v[162:165], v147 offset:3072
	ds_read_b128 v[166:169], v148
	ds_read_b128 v[170:173], v148 offset:1024
	ds_read_b128 v[174:177], v148 offset:2048
	ds_read_b128 v[178:181], v148 offset:3072
	s_add_u32 s16, s50, 0xfff80080
	s_addc_u32 s17, s51, -1
	s_cmp_eq_u32 s77, 28
	s_cselect_b32 s55, s45, s17
	s_cselect_b32 s54, s73, s16
	s_cselect_b32 s53, s31, s76
	s_cselect_b32 s52, s74, s75
	v_lshl_add_u64 v[190:191], s[50:51], 0, v[136:137]
	s_add_i32 m0, s29, 0xc000
	ds_read_b128 v[182:185], v149
	ds_read_b128 v[186:189], v149 offset:1024
	ds_read_b128 v[198:201], v149 offset:2048
	ds_read_b128 v[202:205], v149 offset:3072
	ds_read_b128 v[210:213], v149 offset:4096
	ds_read_b128 v[214:217], v149 offset:5120
	ds_read_b128 v[218:221], v149 offset:6144
	ds_read_b128 v[222:225], v149 offset:7168
	global_load_lds_dwordx4 v[190:191], off
	v_lshl_add_u64 v[190:191], s[50:51], 0, v[138:139]
	s_add_i32 m0, s29, 0xe000
	s_nop 0
	global_load_lds_dwordx4 v[190:191], off
	s_waitcnt vmcnt(8)
	s_waitcnt lgkmcnt(0)
	s_barrier
	s_setprio 1
	s_waitcnt lgkmcnt(0)
	v_mfma_f32_16x16x32_bf16 v[124:127], v[150:153], v[182:185], v[124:127]
	v_mfma_f32_16x16x32_bf16 v[120:123], v[158:161], v[182:185], v[120:123]
	v_mfma_f32_16x16x32_bf16 v[116:119], v[150:153], v[198:201], v[116:119]
	v_mfma_f32_16x16x32_bf16 v[112:115], v[158:161], v[198:201], v[112:115]
	v_mfma_f32_16x16x32_bf16 v[100:103], v[150:153], v[210:213], v[100:103]
	v_mfma_f32_16x16x32_bf16 v[96:99], v[158:161], v[210:213], v[96:99]
	v_mfma_f32_16x16x32_bf16 v[84:87], v[150:153], v[218:221], v[84:87]
	v_mfma_f32_16x16x32_bf16 v[80:83], v[158:161], v[218:221], v[80:83]
	v_mfma_f32_16x16x32_bf16 v[124:127], v[154:157], v[186:189], v[124:127]
	v_mfma_f32_16x16x32_bf16 v[120:123], v[162:165], v[186:189], v[120:123]
	v_mfma_f32_16x16x32_bf16 v[116:119], v[154:157], v[202:205], v[116:119]
	v_mfma_f32_16x16x32_bf16 v[112:115], v[162:165], v[202:205], v[112:115]
	v_mfma_f32_16x16x32_bf16 v[100:103], v[154:157], v[214:217], v[100:103]
	v_mfma_f32_16x16x32_bf16 v[96:99], v[162:165], v[214:217], v[96:99]
	v_mfma_f32_16x16x32_bf16 v[84:87], v[154:157], v[222:225], v[84:87]
	v_mfma_f32_16x16x32_bf16 v[80:83], v[162:165], v[222:225], v[80:83]
	s_setprio 0
	s_setprio 1
	v_mfma_f32_16x16x32_bf16 v[108:111], v[166:169], v[182:185], v[108:111]
	v_mfma_f32_16x16x32_bf16 v[104:107], v[174:177], v[182:185], v[104:107]
	v_mfma_f32_16x16x32_bf16 v[92:95], v[166:169], v[198:201], v[92:95]
	v_mfma_f32_16x16x32_bf16 v[88:91], v[174:177], v[198:201], v[88:91]
	v_mfma_f32_16x16x32_bf16 v[76:79], v[166:169], v[210:213], v[76:79]
	v_mfma_f32_16x16x32_bf16 v[72:75], v[174:177], v[210:213], v[72:75]
	v_mfma_f32_16x16x32_bf16 v[68:71], v[166:169], v[218:221], v[68:71]
	v_mfma_f32_16x16x32_bf16 v[64:67], v[174:177], v[218:221], v[64:67]
	v_mfma_f32_16x16x32_bf16 v[108:111], v[170:173], v[186:189], v[108:111]
	v_mfma_f32_16x16x32_bf16 v[104:107], v[178:181], v[186:189], v[104:107]
	v_mfma_f32_16x16x32_bf16 v[92:95], v[170:173], v[202:205], v[92:95]
	v_mfma_f32_16x16x32_bf16 v[88:91], v[178:181], v[202:205], v[88:91]
	v_mfma_f32_16x16x32_bf16 v[76:79], v[170:173], v[214:217], v[76:79]
	v_mfma_f32_16x16x32_bf16 v[72:75], v[178:181], v[214:217], v[72:75]
	v_mfma_f32_16x16x32_bf16 v[68:71], v[170:173], v[222:225], v[68:71]
	v_mfma_f32_16x16x32_bf16 v[64:67], v[178:181], v[222:225], v[64:67]
	s_setprio 0
	s_barrier
	s_add_i32 s16, s66, s58
	v_lshl_add_u64 v[190:191], s[52:53], 0, v[130:131]
	s_mov_b32 m0, s16
	ds_read_b128 v[182:185], v149 offset:16384
	ds_read_b128 v[186:189], v149 offset:17408
	ds_read_b128 v[198:201], v149 offset:18432
	ds_read_b128 v[202:205], v149 offset:19456
	ds_read_b128 v[210:213], v149 offset:20480
	ds_read_b128 v[214:217], v149 offset:21504
	ds_read_b128 v[218:221], v149 offset:22528
	ds_read_b128 v[222:225], v149 offset:23552
	global_load_lds_dwordx4 v[190:191], off
	s_add_i32 m0, s16, 0x2000
	s_add_u32 s34, s52, 0x80000
	v_lshl_add_u64 v[226:227], s[52:53], 0, v[134:135]
	s_addc_u32 s35, s53, 0
	s_add_i32 s16, s67, s58
	global_load_lds_dwordx4 v[226:227], off
	v_lshl_add_u64 v[228:229], s[34:35], 0, v[130:131]
	s_mov_b32 m0, s16
	v_lshl_add_u64 v[230:231], s[54:55], 0, v[132:133]
	global_load_lds_dwordx4 v[228:229], off
	v_lshl_add_u64 v[228:229], s[34:35], 0, v[134:135]
	s_add_i32 m0, s16, 0x2000
	s_nop 0
	global_load_lds_dwordx4 v[228:229], off
	v_lshl_add_u64 v[228:229], s[54:55], 0, v[128:129]
	s_mov_b32 m0, s29
	s_nop 0
	global_load_lds_dwordx4 v[228:229], off
	s_mov_b32 m0, s59
	s_nop 0
	global_load_lds_dwordx4 v[230:231], off
	s_waitcnt vmcnt(8)
	s_waitcnt lgkmcnt(0)
	s_barrier
; #define PG8_STAGE(bufoff, gbase, voff) do { _Pragma("unroll") for (int _i = 0; _i < 2; ++_i) \
;         __builtin_amdgcn_global_load_lds((const unsigned*)((const char*)(gbase) + (voff)[_i]), (LAS unsigned*)(lds + (bufoff) + ldsw + _i * 8192), 16, 0, 0); } while (0)
; #define PG8_LDA(dst, b, h) do { _Pragma("unroll") for (int m = 0; m < 4; ++m) _Pragma("unroll") for (int k = 0; k < 2; ++k) dst[m][k] = *(const LAS bf16x8*)(lds + PG8_SA(b, h) + aoff + m * 2048 + k * 1024); } while (0)
; #define PG8_LDB(dst, b, h) do { _Pragma("unroll") for (int n = 0; n < 2; ++n) _Pragma("unroll") for (int k = 0; k < 2; ++k) dst[n][k] = *(const LAS bf16x8*)(lds + PG8_SB(b, h) + boff + n * 2048 + k * 1024); } while (0)
; #define PG8_MMA(ai, bj, At, Bt) do { __builtin_amdgcn_s_setprio(1); _Pragma("unroll") for (int m = 0; m < 4; ++m) _Pragma("unroll") for (int n = 0; n < 2; ++n) _Pragma("unroll") for (int k = 0; k < 2; ++k) \
;         acc[ai][bj][m][n] = __builtin_amdgcn_mfma_f32_16x16x32_bf16(Bt[n][k], At[m][k], acc[ai][bj][m][n], 0, 0, 0); __builtin_amdgcn_s_setprio(0); } while (0)
; #define PG8_WAIT_V(n) asm volatile("s_waitcnt vmcnt(" #n ")" ::: "memory")
; #define PG8_WAIT_L(n) asm volatile("s_waitcnt lgkmcnt(" #n ")" ::: "memory")
; #define PG8_BAR __builtin_amdgcn_s_barrier()
; #define PG8_SCHED __builtin_amdgcn_sched_barrier(0)
; template <class Epi, class Sched>
; __device__ __forceinline__ void gemm_phase(LAS unsigned char* lds, const Gemm g, const Sched& S, const Epi& E) {
;     ...
;             PG8_WAIT_V(8); PG8_WAIT_L(0); PG8_BAR; PG8_MMA(1, 0, At, B0); PG8_MMA(1, 1, At, B1); PG8_BAR; PG8_SCHED;
;             PG8_LDB(B0, 1, 0); PG8_LDB(B1, 1, 1); PG8_SCHED; PG8_LDA(At, 1, 0); PG8_STAGE(PG8_SA(0, 1), a2 + hstepA, voffA);
;             PG8_WAIT_V(8); PG8_WAIT_L(0); PG8_BAR; PG8_MMA(0, 0, At, B0); PG8_MMA(0, 1, At, B1); PG8_BAR; PG8_SCHED;
;             PG8_LDA(At, 1, 1); PG8_STAGE(PG8_SB(1, 0), b3, voffB); PG8_STAGE(PG8_SB(1, 1), b3 + hstepB, voffB); PG8_STAGE(PG8_SA(1, 0), a3, voffA);
	s_setprio 1
	s_waitcnt lgkmcnt(0)
	v_mfma_f32_16x16x32_bf16 v[60:63], v[150:153], v[182:185], v[60:63]
	v_mfma_f32_16x16x32_bf16 v[56:59], v[158:161], v[182:185], v[56:59]
	v_mfma_f32_16x16x32_bf16 v[52:55], v[150:153], v[198:201], v[52:55]
	v_mfma_f32_16x16x32_bf16 v[48:51], v[158:161], v[198:201], v[48:51]
	v_mfma_f32_16x16x32_bf16 v[36:39], v[150:153], v[210:213], v[36:39]
	v_mfma_f32_16x16x32_bf16 v[32:35], v[158:161], v[210:213], v[32:35]
	v_mfma_f32_16x16x32_bf16 v[20:23], v[150:153], v[218:221], v[20:23]
	v_mfma_f32_16x16x32_bf16 v[16:19], v[158:161], v[218:221], v[16:19]
	v_mfma_f32_16x16x32_bf16 v[60:63], v[154:157], v[186:189], v[60:63]
	v_mfma_f32_16x16x32_bf16 v[56:59], v[162:165], v[186:189], v[56:59]
	v_mfma_f32_16x16x32_bf16 v[52:55], v[154:157], v[202:205], v[52:55]
	v_mfma_f32_16x16x32_bf16 v[48:51], v[162:165], v[202:205], v[48:51]
	v_mfma_f32_16x16x32_bf16 v[36:39], v[154:157], v[214:217], v[36:39]
	v_mfma_f32_16x16x32_bf16 v[32:35], v[162:165], v[214:217], v[32:35]
	v_mfma_f32_16x16x32_bf16 v[20:23], v[154:157], v[222:225], v[20:23]
	v_mfma_f32_16x16x32_bf16 v[16:19], v[162:165], v[222:225], v[16:19]
	s_setprio 0
	s_setprio 1
	v_mfma_f32_16x16x32_bf16 v[44:47], v[166:169], v[182:185], v[44:47]
	v_mfma_f32_16x16x32_bf16 v[40:43], v[174:177], v[182:185], v[40:43]
	v_mfma_f32_16x16x32_bf16 v[28:31], v[166:169], v[198:201], v[28:31]
	v_mfma_f32_16x16x32_bf16 v[24:27], v[174:177], v[198:201], v[24:27]
	v_mfma_f32_16x16x32_bf16 v[12:15], v[166:169], v[210:213], v[12:15]
	v_mfma_f32_16x16x32_bf16 v[8:11], v[174:177], v[210:213], v[8:11]
	v_mfma_f32_16x16x32_bf16 v[4:7], v[166:169], v[218:221], v[4:7]
	v_mfma_f32_16x16x32_bf16 v[0:3], v[174:177], v[218:221], v[0:3]
	v_mfma_f32_16x16x32_bf16 v[44:47], v[170:173], v[186:189], v[44:47]
	v_mfma_f32_16x16x32_bf16 v[40:43], v[178:181], v[186:189], v[40:43]
	v_mfma_f32_16x16x32_bf16 v[28:31], v[170:173], v[202:205], v[28:31]
	v_mfma_f32_16x16x32_bf16 v[24:27], v[178:181], v[202:205], v[24:27]
	v_mfma_f32_16x16x32_bf16 v[12:15], v[170:173], v[214:217], v[12:15]
	v_mfma_f32_16x16x32_bf16 v[8:11], v[178:181], v[214:217], v[8:11]
	v_mfma_f32_16x16x32_bf16 v[4:7], v[170:173], v[222:225], v[4:7]
	v_mfma_f32_16x16x32_bf16 v[0:3], v[178:181], v[222:225], v[0:3]
	s_setprio 0
	s_barrier
	s_add_i32 s16, 0, 0x18000
	s_add_i32 s17, 0, 0x1c000
	v_add_u32_e32 v162, s16, v145
	v_add_u32_e32 v178, s17, v145
	ds_read_b128 v[150:153], v162
	ds_read_b128 v[154:157], v162 offset:1024
	ds_read_b128 v[158:161], v162 offset:2048
	ds_read_b128 v[162:165], v162 offset:3072
	ds_read_b128 v[166:169], v178
	ds_read_b128 v[170:173], v178 offset:1024
	ds_read_b128 v[174:177], v178 offset:2048
	ds_read_b128 v[178:181], v178 offset:3072
	s_add_u32 s34, s54, 0x80000
	s_addc_u32 s35, s55, 0
	s_mov_b32 m0, s60
	v_lshl_add_u64 v[232:233], s[34:35], 0, v[128:129]
	ds_read_b128 v[182:185], v149 offset:32768
	ds_read_b128 v[186:189], v149 offset:33792
	ds_read_b128 v[198:201], v149 offset:34816
	ds_read_b128 v[202:205], v149 offset:35840
	ds_read_b128 v[210:213], v149 offset:36864
	ds_read_b128 v[214:217], v149 offset:37888
	ds_read_b128 v[218:221], v149 offset:38912
	ds_read_b128 v[222:225], v149 offset:39936
	global_load_lds_dwordx4 v[232:233], off
	v_lshl_add_u64 v[232:233], s[34:35], 0, v[132:133]
	s_mov_b32 m0, s61
	s_nop 0
	global_load_lds_dwordx4 v[232:233], off
	s_waitcnt vmcnt(8)
	s_waitcnt lgkmcnt(0)
	s_barrier
	s_setprio 1
	s_waitcnt lgkmcnt(0)
	v_mfma_f32_16x16x32_bf16 v[124:127], v[150:153], v[182:185], v[124:127]
	v_mfma_f32_16x16x32_bf16 v[120:123], v[158:161], v[182:185], v[120:123]
	v_mfma_f32_16x16x32_bf16 v[116:119], v[150:153], v[198:201], v[116:119]
	v_mfma_f32_16x16x32_bf16 v[112:115], v[158:161], v[198:201], v[112:115]
	v_mfma_f32_16x16x32_bf16 v[100:103], v[150:153], v[210:213], v[100:103]
	v_mfma_f32_16x16x32_bf16 v[96:99], v[158:161], v[210:213], v[96:99]
	v_mfma_f32_16x16x32_bf16 v[84:87], v[150:153], v[218:221], v[84:87]
	v_mfma_f32_16x16x32_bf16 v[80:83], v[158:161], v[218:221], v[80:83]
	v_mfma_f32_16x16x32_bf16 v[124:127], v[154:157], v[186:189], v[124:127]
	v_mfma_f32_16x16x32_bf16 v[120:123], v[162:165], v[186:189], v[120:123]
	v_mfma_f32_16x16x32_bf16 v[116:119], v[154:157], v[202:205], v[116:119]
	v_mfma_f32_16x16x32_bf16 v[112:115], v[162:165], v[202:205], v[112:115]
	v_mfma_f32_16x16x32_bf16 v[100:103], v[154:157], v[214:217], v[100:103]
	v_mfma_f32_16x16x32_bf16 v[96:99], v[162:165], v[214:217], v[96:99]
	v_mfma_f32_16x16x32_bf16 v[84:87], v[154:157], v[222:225], v[84:87]
	v_mfma_f32_16x16x32_bf16 v[80:83], v[162:165], v[222:225], v[80:83]
	s_setprio 0
	s_setprio 1
	v_mfma_f32_16x16x32_bf16 v[108:111], v[166:169], v[182:185], v[108:111]
	v_mfma_f32_16x16x32_bf16 v[104:107], v[174:177], v[182:185], v[104:107]
	v_mfma_f32_16x16x32_bf16 v[92:95], v[166:169], v[198:201], v[92:95]
	v_mfma_f32_16x16x32_bf16 v[88:91], v[174:177], v[198:201], v[88:91]
	v_mfma_f32_16x16x32_bf16 v[76:79], v[166:169], v[210:213], v[76:79]
	v_mfma_f32_16x16x32_bf16 v[72:75], v[174:177], v[210:213], v[72:75]
	v_mfma_f32_16x16x32_bf16 v[68:71], v[166:169], v[218:221], v[68:71]
	v_mfma_f32_16x16x32_bf16 v[64:67], v[174:177], v[218:221], v[64:67]
	v_mfma_f32_16x16x32_bf16 v[108:111], v[170:173], v[186:189], v[108:111]
	v_mfma_f32_16x16x32_bf16 v[104:107], v[178:181], v[186:189], v[104:107]
	v_mfma_f32_16x16x32_bf16 v[92:95], v[170:173], v[202:205], v[92:95]
	v_mfma_f32_16x16x32_bf16 v[88:91], v[178:181], v[202:205], v[88:91]
	v_mfma_f32_16x16x32_bf16 v[76:79], v[170:173], v[214:217], v[76:79]
	v_mfma_f32_16x16x32_bf16 v[72:75], v[178:181], v[214:217], v[72:75]
	v_mfma_f32_16x16x32_bf16 v[68:71], v[170:173], v[222:225], v[68:71]
	v_mfma_f32_16x16x32_bf16 v[64:67], v[178:181], v[222:225], v[64:67]
	s_setprio 0
	s_barrier
; #define PG8_STAGE(bufoff, gbase, voff) do { _Pragma("unroll") for (int _i = 0; _i < 2; ++_i) \
;         __builtin_amdgcn_global_load_lds((const unsigned*)((const char*)(gbase) + (voff)[_i]), (LAS unsigned*)(lds + (bufoff) + ldsw + _i * 8192), 16, 0, 0); } while (0)
; #define PG8_LDA(dst, b, h) do { _Pragma("unroll") for (int m = 0; m < 4; ++m) _Pragma("unroll") for (int k = 0; k < 2; ++k) dst[m][k] = *(const LAS bf16x8*)(lds + PG8_SA(b, h) + aoff + m * 2048 + k * 1024); } while (0)
; #define PG8_LDB(dst, b, h) do { _Pragma("unroll") for (int n = 0; n < 2; ++n) _Pragma("unroll") for (int k = 0; k < 2; ++k) dst[n][k] = *(const LAS bf16x8*)(lds + PG8_SB(b, h) + boff + n * 2048 + k * 1024); } while (0)
; #define PG8_WAIT_V(n) asm volatile("s_waitcnt vmcnt(" #n ")" ::: "memory")
; #define PG8_BAR __builtin_amdgcn_s_barrier()
; template <class Epi, class Sched>
; __device__ __forceinline__ void gemm_phase(LAS unsigned char* lds, const Gemm g, const Sched& S, const Epi& E) {
;     ...
;         for (int t = 0; t < nt; t += 2) {
;             const bool last = (t == nt - 2);
;             const char* a1 = cA + (size_t)(t + 1) * kstep;
;             const char* a2 = last ? nA : cA + (size_t)(t + 2) * kstep; const char* b2 = last ? nB : cB + (size_t)(t + 2) * kstep;
;             const char* a3 = a2 + kstep; const char* b3 = b2 + kstep;
;             PG8_LDB(B0, 0, 0); PG8_LDB(B1, 0, 1); PG8_SCHED; PG8_LDA(At, 0, 0); PG8_STAGE(PG8_SA(1, 1), a1 + hstepA, voffA);
;             PG8_WAIT_V(8); PG8_WAIT_L(0); PG8_BAR; PG8_MMA(0, 0, At, B0); PG8_MMA(0, 1, At, B1); PG8_BAR; PG8_SCHED;
;             PG8_LDA(At, 0, 1); PG8_STAGE(PG8_SB(0, 0), b2, voffB); PG8_STAGE(PG8_SB(0, 1), b2 + hstepB, voffB); PG8_STAGE(PG8_SA(0, 0), a2, voffA);
;             PG8_WAIT_V(8); PG8_WAIT_L(0); PG8_BAR; PG8_MMA(1, 0, At, B0); PG8_MMA(1, 1, At, B1); PG8_BAR; PG8_SCHED;
;             PG8_LDB(B0, 1, 0); PG8_LDB(B1, 1, 1); PG8_SCHED; PG8_LDA(At, 1, 0); PG8_STAGE(PG8_SA(0, 1), a2 + hstepA, voffA);
;             PG8_WAIT_V(8); PG8_WAIT_L(0); PG8_BAR; PG8_MMA(0, 0, At, B0); PG8_MMA(0, 1, At, B1); PG8_BAR; PG8_SCHED;
;             PG8_LDA(At, 1, 1); PG8_STAGE(PG8_SB(1, 0), b3, voffB); PG8_STAGE(PG8_SB(1, 1), b3 + hstepB, voffB); PG8_STAGE(PG8_SA(1, 0), a3, voffA);
;             PG8_WAIT_V(8); PG8_WAIT_L(0); PG8_BAR; PG8_MMA(1, 0, At, B0); PG8_MMA(1, 1, At, B1); PG8_BAR; PG8_SCHED;
	s_add_i32 s16, s16, s58
	v_lshl_add_u64 v[190:191], v[190:191], 0, s[10:11]
	s_mov_b32 m0, s16
	ds_read_b128 v[182:185], v149 offset:49152
	ds_read_b128 v[186:189], v149 offset:50176
	ds_read_b128 v[198:201], v149 offset:51200
	ds_read_b128 v[202:205], v149 offset:52224
	ds_read_b128 v[210:213], v149 offset:53248
	ds_read_b128 v[214:217], v149 offset:54272
	ds_read_b128 v[218:221], v149 offset:55296
	ds_read_b128 v[222:225], v149 offset:56320
	global_load_lds_dwordx4 v[190:191], off
	s_add_i32 m0, s16, 0x2000
	s_add_u32 s34, s52, 0x80080
	v_lshl_add_u64 v[190:191], v[226:227], 0, s[10:11]
	s_addc_u32 s35, s53, 0
	s_add_i32 s16, s17, s58
	global_load_lds_dwordx4 v[190:191], off
	v_lshl_add_u64 v[190:191], s[34:35], 0, v[130:131]
	s_mov_b32 m0, s16
	s_nop 0
	global_load_lds_dwordx4 v[190:191], off
	v_lshl_add_u64 v[190:191], s[34:35], 0, v[134:135]
	s_add_i32 m0, s16, 0x2000
	s_nop 0
	global_load_lds_dwordx4 v[190:191], off
	v_lshl_add_u64 v[190:191], v[228:229], 0, s[10:11]
	s_mov_b32 m0, s63
	s_nop 0
	global_load_lds_dwordx4 v[190:191], off
	v_lshl_add_u64 v[190:191], v[230:231], 0, s[10:11]
	s_mov_b32 m0, s64
	s_nop 0
	global_load_lds_dwordx4 v[190:191], off
	s_waitcnt vmcnt(8)
	s_waitcnt lgkmcnt(0)
	s_barrier
	s_setprio 1
	s_waitcnt lgkmcnt(0)
	v_mfma_f32_16x16x32_bf16 v[60:63], v[150:153], v[182:185], v[60:63]
	v_mfma_f32_16x16x32_bf16 v[56:59], v[158:161], v[182:185], v[56:59]
	v_mfma_f32_16x16x32_bf16 v[52:55], v[150:153], v[198:201], v[52:55]
	v_mfma_f32_16x16x32_bf16 v[48:51], v[158:161], v[198:201], v[48:51]
	v_mfma_f32_16x16x32_bf16 v[36:39], v[150:153], v[210:213], v[36:39]
	v_mfma_f32_16x16x32_bf16 v[32:35], v[158:161], v[210:213], v[32:35]
	v_mfma_f32_16x16x32_bf16 v[20:23], v[150:153], v[218:221], v[20:23]
	v_mfma_f32_16x16x32_bf16 v[16:19], v[158:161], v[218:221], v[16:19]
	v_mfma_f32_16x16x32_bf16 v[60:63], v[154:157], v[186:189], v[60:63]
	v_mfma_f32_16x16x32_bf16 v[56:59], v[162:165], v[186:189], v[56:59]
	v_mfma_f32_16x16x32_bf16 v[52:55], v[154:157], v[202:205], v[52:55]
	v_mfma_f32_16x16x32_bf16 v[48:51], v[162:165], v[202:205], v[48:51]
	v_mfma_f32_16x16x32_bf16 v[36:39], v[154:157], v[214:217], v[36:39]
	v_mfma_f32_16x16x32_bf16 v[32:35], v[162:165], v[214:217], v[32:35]
	v_mfma_f32_16x16x32_bf16 v[20:23], v[154:157], v[222:225], v[20:23]
	v_mfma_f32_16x16x32_bf16 v[16:19], v[162:165], v[222:225], v[16:19]
	s_setprio 0
	s_setprio 1
	v_mfma_f32_16x16x32_bf16 v[44:47], v[166:169], v[182:185], v[44:47]
	v_mfma_f32_16x16x32_bf16 v[40:43], v[174:177], v[182:185], v[40:43]
	v_mfma_f32_16x16x32_bf16 v[28:31], v[166:169], v[198:201], v[28:31]
	v_mfma_f32_16x16x32_bf16 v[24:27], v[174:177], v[198:201], v[24:27]
	v_mfma_f32_16x16x32_bf16 v[12:15], v[166:169], v[210:213], v[12:15]
	v_mfma_f32_16x16x32_bf16 v[8:11], v[174:177], v[210:213], v[8:11]
	v_mfma_f32_16x16x32_bf16 v[4:7], v[166:169], v[218:221], v[4:7]
	v_mfma_f32_16x16x32_bf16 v[0:3], v[174:177], v[218:221], v[0:3]
	v_mfma_f32_16x16x32_bf16 v[44:47], v[170:173], v[186:189], v[44:47]
	v_mfma_f32_16x16x32_bf16 v[40:43], v[178:181], v[186:189], v[40:43]
	v_mfma_f32_16x16x32_bf16 v[28:31], v[170:173], v[202:205], v[28:31]
	v_mfma_f32_16x16x32_bf16 v[24:27], v[178:181], v[202:205], v[24:27]
	v_mfma_f32_16x16x32_bf16 v[12:15], v[170:173], v[214:217], v[12:15]
	v_mfma_f32_16x16x32_bf16 v[8:11], v[178:181], v[214:217], v[8:11]
	v_mfma_f32_16x16x32_bf16 v[4:7], v[170:173], v[222:225], v[4:7]
	v_mfma_f32_16x16x32_bf16 v[0:3], v[178:181], v[222:225], v[0:3]
	s_setprio 0
	s_add_i32 s77, s77, 2
	s_add_u32 s50, s50, 0x100
	s_addc_u32 s51, s51, 0
	s_add_u32 s75, s75, 0x100
	s_addc_u32 s76, s76, 0
	s_cmp_gt_u32 s77, 29
	s_barrier
	s_cbranch_scc0 .LBB0_633
	s_and_b64 vcc, exec, s[12:13]
	s_cbranch_vccz .LBB0_636
	s_barrier

; #define PG8_STAGE(bufoff, gbase, voff) do { _Pragma("unroll") for (int _i = 0; _i < 2; ++_i) \
;         __builtin_amdgcn_global_load_lds((const unsigned*)((const char*)(gbase) + (voff)[_i]), (LAS unsigned*)(lds + (bufoff) + ldsw + _i * 8192), 16, 0, 0); } while (0)
; #define PG8_LDA(dst, b, h) do { _Pragma("unroll") for (int m = 0; m < 4; ++m) _Pragma("unroll") for (int k = 0; k < 2; ++k) dst[m][k] = *(const LAS bf16x8*)(lds + PG8_SA(b, h) + aoff + m * 2048 + k * 1024); } while (0)
; #define PG8_LDB(dst, b, h) do { _Pragma("unroll") for (int n = 0; n < 2; ++n) _Pragma("unroll") for (int k = 0; k < 2; ++k) dst[n][k] = *(const LAS bf16x8*)(lds + PG8_SB(b, h) + boff + n * 2048 + k * 1024); } while (0)
; #define PG8_MMA(ai, bj, At, Bt) do { __builtin_amdgcn_s_setprio(1); _Pragma("unroll") for (int m = 0; m < 4; ++m) _Pragma("unroll") for (int n = 0; n < 2; ++n) _Pragma("unroll") for (int k = 0; k < 2; ++k) \
;         acc[ai][bj][m][n] = __builtin_amdgcn_mfma_f32_16x16x32_bf16(Bt[n][k], At[m][k], acc[ai][bj][m][n], 0, 0, 0); __builtin_amdgcn_s_setprio(0); } while (0)
; #define PG8_WAIT_V(n) asm volatile("s_waitcnt vmcnt(" #n ")" ::: "memory")
; #define PG8_WAIT_L(n) asm volatile("s_waitcnt lgkmcnt(" #n ")" ::: "memory")
; #define PG8_BAR __builtin_amdgcn_s_barrier()
; #define PG8_SCHED __builtin_amdgcn_sched_barrier(0)
; template <class Epi, class Sched>
; __device__ __forceinline__ void gemm_phase(LAS unsigned char* lds, const Gemm g, const Sched& S, const Epi& E) {
;     ...
;             PG8_LDB(B0, 0, 0); PG8_LDB(B1, 0, 1); PG8_SCHED; PG8_LDA(At, 0, 0); PG8_STAGE(PG8_SA(1, 1), a1 + hstepA, voffA);
;             PG8_WAIT_V(8); PG8_WAIT_L(0); PG8_BAR; PG8_MMA(0, 0, At, B0); PG8_MMA(0, 1, At, B1); PG8_BAR; PG8_SCHED;
;             PG8_LDA(At, 0, 1); PG8_STAGE(PG8_SB(0, 0), b2, voffB); PG8_STAGE(PG8_SB(0, 1), b2 + hstepB, voffB); PG8_STAGE(PG8_SA(0, 0), a2, voffA);
;             PG8_WAIT_V(8); PG8_WAIT_L(0); PG8_BAR; PG8_MMA(1, 0, At, B0); PG8_MMA(1, 1, At, B1); PG8_BAR; PG8_SCHED;
.LBB0_725:
	ds_read_b128 v[140:143], v149
	ds_read_b128 v[154:157], v149 offset:1024
	ds_read_b128 v[158:161], v149 offset:2048
	ds_read_b128 v[162:165], v149 offset:3072
	ds_read_b128 v[166:169], v150
	ds_read_b128 v[170:173], v150 offset:1024
	ds_read_b128 v[174:177], v150 offset:2048
	ds_read_b128 v[178:181], v150 offset:3072
	s_add_u32 s16, s52, 0xfffe0080
	s_addc_u32 s17, s53, -1
	s_cmp_eq_u32 s73, 4
	s_cselect_b32 s57, s11, s17
	s_cselect_b32 s56, s45, s16
	s_cselect_b32 s55, s31, s72
	s_cselect_b32 s54, s51, s71
	v_lshl_add_u64 v[190:191], s[52:53], 0, v[132:133]
	s_add_i32 m0, s60, 0xc000
	ds_read_b128 v[182:185], v151
	ds_read_b128 v[186:189], v151 offset:1024
	ds_read_b128 v[198:201], v151 offset:2048
	ds_read_b128 v[202:205], v151 offset:3072
	ds_read_b128 v[210:213], v151 offset:4096
	ds_read_b128 v[214:217], v151 offset:5120
	ds_read_b128 v[218:221], v151 offset:6144
	ds_read_b128 v[222:225], v151 offset:7168
	global_load_lds_dwordx4 v[190:191], off
	v_lshl_add_u64 v[190:191], s[52:53], 0, v[134:135]
	s_add_i32 m0, s60, 0xe000
	s_nop 0
	global_load_lds_dwordx4 v[190:191], off
	s_waitcnt vmcnt(8)
	s_waitcnt lgkmcnt(0)
	s_barrier
	s_setprio 1
	s_waitcnt lgkmcnt(0)
	v_mfma_f32_16x16x32_bf16 v[124:127], v[140:143], v[182:185], v[124:127]
	v_mfma_f32_16x16x32_bf16 v[120:123], v[158:161], v[182:185], v[120:123]
	v_mfma_f32_16x16x32_bf16 v[108:111], v[140:143], v[198:201], v[108:111]
	v_mfma_f32_16x16x32_bf16 v[104:107], v[158:161], v[198:201], v[104:107]
	v_mfma_f32_16x16x32_bf16 v[92:95], v[140:143], v[210:213], v[92:95]
	v_mfma_f32_16x16x32_bf16 v[88:91], v[158:161], v[210:213], v[88:91]
	v_mfma_f32_16x16x32_bf16 v[76:79], v[140:143], v[218:221], v[76:79]
	v_mfma_f32_16x16x32_bf16 v[72:75], v[158:161], v[218:221], v[72:75]
	v_mfma_f32_16x16x32_bf16 v[124:127], v[154:157], v[186:189], v[124:127]
	v_mfma_f32_16x16x32_bf16 v[120:123], v[162:165], v[186:189], v[120:123]
	v_mfma_f32_16x16x32_bf16 v[108:111], v[154:157], v[202:205], v[108:111]
	v_mfma_f32_16x16x32_bf16 v[104:107], v[162:165], v[202:205], v[104:107]
	v_mfma_f32_16x16x32_bf16 v[92:95], v[154:157], v[214:217], v[92:95]
	v_mfma_f32_16x16x32_bf16 v[88:91], v[162:165], v[214:217], v[88:91]
	v_mfma_f32_16x16x32_bf16 v[76:79], v[154:157], v[222:225], v[76:79]
	v_mfma_f32_16x16x32_bf16 v[72:75], v[162:165], v[222:225], v[72:75]
	s_setprio 0
	s_setprio 1
	v_mfma_f32_16x16x32_bf16 v[116:119], v[166:169], v[182:185], v[116:119]
	v_mfma_f32_16x16x32_bf16 v[112:115], v[174:177], v[182:185], v[112:115]
	v_mfma_f32_16x16x32_bf16 v[100:103], v[166:169], v[198:201], v[100:103]
	v_mfma_f32_16x16x32_bf16 v[96:99], v[174:177], v[198:201], v[96:99]
	v_mfma_f32_16x16x32_bf16 v[84:87], v[166:169], v[210:213], v[84:87]
	v_mfma_f32_16x16x32_bf16 v[80:83], v[174:177], v[210:213], v[80:83]
	v_mfma_f32_16x16x32_bf16 v[68:71], v[166:169], v[218:221], v[68:71]
	v_mfma_f32_16x16x32_bf16 v[64:67], v[174:177], v[218:221], v[64:67]
	v_mfma_f32_16x16x32_bf16 v[116:119], v[170:173], v[186:189], v[116:119]
	v_mfma_f32_16x16x32_bf16 v[112:115], v[178:181], v[186:189], v[112:115]
	v_mfma_f32_16x16x32_bf16 v[100:103], v[170:173], v[202:205], v[100:103]
	v_mfma_f32_16x16x32_bf16 v[96:99], v[178:181], v[202:205], v[96:99]
	v_mfma_f32_16x16x32_bf16 v[84:87], v[170:173], v[214:217], v[84:87]
	v_mfma_f32_16x16x32_bf16 v[80:83], v[178:181], v[214:217], v[80:83]
	v_mfma_f32_16x16x32_bf16 v[68:71], v[170:173], v[222:225], v[68:71]
	v_mfma_f32_16x16x32_bf16 v[64:67], v[178:181], v[222:225], v[64:67]
	s_setprio 0
	s_barrier
	s_add_i32 s16, s69, s59
	v_lshl_add_u64 v[190:191], s[54:55], 0, v[128:129]
	s_mov_b32 m0, s16
	ds_read_b128 v[182:185], v151 offset:16384
	ds_read_b128 v[186:189], v151 offset:17408
	ds_read_b128 v[198:201], v151 offset:18432
	ds_read_b128 v[202:205], v151 offset:19456
	ds_read_b128 v[210:213], v151 offset:20480
	ds_read_b128 v[214:217], v151 offset:21504
	ds_read_b128 v[218:221], v151 offset:22528
	ds_read_b128 v[222:225], v151 offset:23552
	global_load_lds_dwordx4 v[190:191], off
	s_add_i32 m0, s16, 0x2000
	s_add_u32 s34, s54, 0x20000
	v_lshl_add_u64 v[226:227], s[54:55], 0, v[130:131]
	s_addc_u32 s35, s55, 0
	s_add_i32 s16, s70, s59
	global_load_lds_dwordx4 v[226:227], off
	v_lshl_add_u64 v[228:229], s[34:35], 0, v[128:129]
	s_mov_b32 m0, s16
	v_lshl_add_u64 v[230:231], s[56:57], 0, v[130:131]
	global_load_lds_dwordx4 v[228:229], off
	v_lshl_add_u64 v[228:229], s[34:35], 0, v[130:131]
	s_add_i32 m0, s16, 0x2000
	s_nop 0
	global_load_lds_dwordx4 v[228:229], off
	v_lshl_add_u64 v[228:229], s[56:57], 0, v[128:129]
	s_mov_b32 m0, s60
	s_nop 0
	global_load_lds_dwordx4 v[228:229], off
	s_mov_b32 m0, s61
	s_nop 0
	global_load_lds_dwordx4 v[230:231], off
	s_waitcnt vmcnt(8)
	s_waitcnt lgkmcnt(0)
	s_barrier
; #define PG8_STAGE(bufoff, gbase, voff) do { _Pragma("unroll") for (int _i = 0; _i < 2; ++_i) \
;         __builtin_amdgcn_global_load_lds((const unsigned*)((const char*)(gbase) + (voff)[_i]), (LAS unsigned*)(lds + (bufoff) + ldsw + _i * 8192), 16, 0, 0); } while (0)
; #define PG8_LDA(dst, b, h) do { _Pragma("unroll") for (int m = 0; m < 4; ++m) _Pragma("unroll") for (int k = 0; k < 2; ++k) dst[m][k] = *(const LAS bf16x8*)(lds + PG8_SA(b, h) + aoff + m * 2048 + k * 1024); } while (0)
; #define PG8_LDB(dst, b, h) do { _Pragma("unroll") for (int n = 0; n < 2; ++n) _Pragma("unroll") for (int k = 0; k < 2; ++k) dst[n][k] = *(const LAS bf16x8*)(lds + PG8_SB(b, h) + boff + n * 2048 + k * 1024); } while (0)
; #define PG8_MMA(ai, bj, At, Bt) do { __builtin_amdgcn_s_setprio(1); _Pragma("unroll") for (int m = 0; m < 4; ++m) _Pragma("unroll") for (int n = 0; n < 2; ++n) _Pragma("unroll") for (int k = 0; k < 2; ++k) \
;         acc[ai][bj][m][n] = __builtin_amdgcn_mfma_f32_16x16x32_bf16(Bt[n][k], At[m][k], acc[ai][bj][m][n], 0, 0, 0); __builtin_amdgcn_s_setprio(0); } while (0)
; #define PG8_WAIT_V(n) asm volatile("s_waitcnt vmcnt(" #n ")" ::: "memory")
; #define PG8_WAIT_L(n) asm volatile("s_waitcnt lgkmcnt(" #n ")" ::: "memory")
; #define PG8_BAR __builtin_amdgcn_s_barrier()
; #define PG8_SCHED __builtin_amdgcn_sched_barrier(0)
; template <class Epi, class Sched>
; __device__ __forceinline__ void gemm_phase(LAS unsigned char* lds, const Gemm g, const Sched& S, const Epi& E) {
;     ...
;             PG8_WAIT_V(8); PG8_WAIT_L(0); PG8_BAR; PG8_MMA(1, 0, At, B0); PG8_MMA(1, 1, At, B1); PG8_BAR; PG8_SCHED;
;             PG8_LDB(B0, 1, 0); PG8_LDB(B1, 1, 1); PG8_SCHED; PG8_LDA(At, 1, 0); PG8_STAGE(PG8_SA(0, 1), a2 + hstepA, voffA);
;             PG8_WAIT_V(8); PG8_WAIT_L(0); PG8_BAR; PG8_MMA(0, 0, At, B0); PG8_MMA(0, 1, At, B1); PG8_BAR; PG8_SCHED;
;             PG8_LDA(At, 1, 1); PG8_STAGE(PG8_SB(1, 0), b3, voffB); PG8_STAGE(PG8_SB(1, 1), b3 + hstepB, voffB); PG8_STAGE(PG8_SA(1, 0), a3, voffA);
	s_setprio 1
	s_waitcnt lgkmcnt(0)
	v_mfma_f32_16x16x32_bf16 v[60:63], v[140:143], v[182:185], v[60:63]
	v_mfma_f32_16x16x32_bf16 v[56:59], v[158:161], v[182:185], v[56:59]
	v_mfma_f32_16x16x32_bf16 v[44:47], v[140:143], v[198:201], v[44:47]
	v_mfma_f32_16x16x32_bf16 v[40:43], v[158:161], v[198:201], v[40:43]
	v_mfma_f32_16x16x32_bf16 v[28:31], v[140:143], v[210:213], v[28:31]
	v_mfma_f32_16x16x32_bf16 v[24:27], v[158:161], v[210:213], v[24:27]
	v_mfma_f32_16x16x32_bf16 v[12:15], v[140:143], v[218:221], v[12:15]
	v_mfma_f32_16x16x32_bf16 v[8:11], v[158:161], v[218:221], v[8:11]
	v_mfma_f32_16x16x32_bf16 v[60:63], v[154:157], v[186:189], v[60:63]
	v_mfma_f32_16x16x32_bf16 v[56:59], v[162:165], v[186:189], v[56:59]
	v_mfma_f32_16x16x32_bf16 v[44:47], v[154:157], v[202:205], v[44:47]
	v_mfma_f32_16x16x32_bf16 v[40:43], v[162:165], v[202:205], v[40:43]
	v_mfma_f32_16x16x32_bf16 v[28:31], v[154:157], v[214:217], v[28:31]
	v_mfma_f32_16x16x32_bf16 v[24:27], v[162:165], v[214:217], v[24:27]
	v_mfma_f32_16x16x32_bf16 v[12:15], v[154:157], v[222:225], v[12:15]
	v_mfma_f32_16x16x32_bf16 v[8:11], v[162:165], v[222:225], v[8:11]
	s_setprio 0
	s_setprio 1
	v_mfma_f32_16x16x32_bf16 v[52:55], v[166:169], v[182:185], v[52:55]
	v_mfma_f32_16x16x32_bf16 v[48:51], v[174:177], v[182:185], v[48:51]
	v_mfma_f32_16x16x32_bf16 v[36:39], v[166:169], v[198:201], v[36:39]
	v_mfma_f32_16x16x32_bf16 v[32:35], v[174:177], v[198:201], v[32:35]
	v_mfma_f32_16x16x32_bf16 v[20:23], v[166:169], v[210:213], v[20:23]
	v_mfma_f32_16x16x32_bf16 v[16:19], v[174:177], v[210:213], v[16:19]
	v_mfma_f32_16x16x32_bf16 v[4:7], v[166:169], v[218:221], v[4:7]
	v_mfma_f32_16x16x32_bf16 v[0:3], v[174:177], v[218:221], v[0:3]
	v_mfma_f32_16x16x32_bf16 v[52:55], v[170:173], v[186:189], v[52:55]
	v_mfma_f32_16x16x32_bf16 v[48:51], v[178:181], v[186:189], v[48:51]
	v_mfma_f32_16x16x32_bf16 v[36:39], v[170:173], v[202:205], v[36:39]
	v_mfma_f32_16x16x32_bf16 v[32:35], v[178:181], v[202:205], v[32:35]
	v_mfma_f32_16x16x32_bf16 v[20:23], v[170:173], v[214:217], v[20:23]
	v_mfma_f32_16x16x32_bf16 v[16:19], v[178:181], v[214:217], v[16:19]
	v_mfma_f32_16x16x32_bf16 v[4:7], v[170:173], v[222:225], v[4:7]
	v_mfma_f32_16x16x32_bf16 v[0:3], v[178:181], v[222:225], v[0:3]
	s_setprio 0
	s_barrier
	s_add_i32 s16, 0, 0x18000
	v_add_u32_e32 v153, s16, v145
	s_add_i32 s17, 0, 0x1c000
	ds_read_b128 v[140:143], v153
	ds_read_b128 v[154:157], v153 offset:1024
	ds_read_b128 v[158:161], v153 offset:2048
	ds_read_b128 v[162:165], v153 offset:3072
	v_add_u32_e32 v153, s17, v145
	ds_read_b128 v[166:169], v153
	ds_read_b128 v[170:173], v153 offset:1024
	ds_read_b128 v[174:177], v153 offset:2048
	ds_read_b128 v[178:181], v153 offset:3072
	s_add_u32 s34, s56, 0x20000
	s_addc_u32 s35, s57, 0
	s_mov_b32 m0, s62
	v_lshl_add_u64 v[232:233], s[34:35], 0, v[128:129]
	ds_read_b128 v[182:185], v151 offset:32768
	ds_read_b128 v[186:189], v151 offset:33792
	ds_read_b128 v[198:201], v151 offset:34816
	ds_read_b128 v[202:205], v151 offset:35840
	ds_read_b128 v[210:213], v151 offset:36864
	ds_read_b128 v[214:217], v151 offset:37888
	ds_read_b128 v[218:221], v151 offset:38912
	ds_read_b128 v[222:225], v151 offset:39936
	global_load_lds_dwordx4 v[232:233], off
	v_lshl_add_u64 v[232:233], s[34:35], 0, v[130:131]
	s_mov_b32 m0, s63
	s_nop 0
	global_load_lds_dwordx4 v[232:233], off
	s_waitcnt vmcnt(8)
	s_waitcnt lgkmcnt(0)
	s_barrier
	s_setprio 1
	s_waitcnt lgkmcnt(0)
	v_mfma_f32_16x16x32_bf16 v[124:127], v[140:143], v[182:185], v[124:127]
	v_mfma_f32_16x16x32_bf16 v[120:123], v[158:161], v[182:185], v[120:123]
	v_mfma_f32_16x16x32_bf16 v[108:111], v[140:143], v[198:201], v[108:111]
	v_mfma_f32_16x16x32_bf16 v[104:107], v[158:161], v[198:201], v[104:107]
	v_mfma_f32_16x16x32_bf16 v[92:95], v[140:143], v[210:213], v[92:95]
	v_mfma_f32_16x16x32_bf16 v[88:91], v[158:161], v[210:213], v[88:91]
	v_mfma_f32_16x16x32_bf16 v[76:79], v[140:143], v[218:221], v[76:79]
	v_mfma_f32_16x16x32_bf16 v[72:75], v[158:161], v[218:221], v[72:75]
	v_mfma_f32_16x16x32_bf16 v[124:127], v[154:157], v[186:189], v[124:127]
	v_mfma_f32_16x16x32_bf16 v[120:123], v[162:165], v[186:189], v[120:123]
	v_mfma_f32_16x16x32_bf16 v[108:111], v[154:157], v[202:205], v[108:111]
	v_mfma_f32_16x16x32_bf16 v[104:107], v[162:165], v[202:205], v[104:107]
	v_mfma_f32_16x16x32_bf16 v[92:95], v[154:157], v[214:217], v[92:95]
	v_mfma_f32_16x16x32_bf16 v[88:91], v[162:165], v[214:217], v[88:91]
	v_mfma_f32_16x16x32_bf16 v[76:79], v[154:157], v[222:225], v[76:79]
	v_mfma_f32_16x16x32_bf16 v[72:75], v[162:165], v[222:225], v[72:75]
	s_setprio 0
	s_setprio 1
	v_mfma_f32_16x16x32_bf16 v[116:119], v[166:169], v[182:185], v[116:119]
	v_mfma_f32_16x16x32_bf16 v[112:115], v[174:177], v[182:185], v[112:115]
	v_mfma_f32_16x16x32_bf16 v[100:103], v[166:169], v[198:201], v[100:103]
	v_mfma_f32_16x16x32_bf16 v[96:99], v[174:177], v[198:201], v[96:99]
	v_mfma_f32_16x16x32_bf16 v[84:87], v[166:169], v[210:213], v[84:87]
	v_mfma_f32_16x16x32_bf16 v[80:83], v[174:177], v[210:213], v[80:83]
	v_mfma_f32_16x16x32_bf16 v[68:71], v[166:169], v[218:221], v[68:71]
	v_mfma_f32_16x16x32_bf16 v[64:67], v[174:177], v[218:221], v[64:67]
	v_mfma_f32_16x16x32_bf16 v[116:119], v[170:173], v[186:189], v[116:119]
	v_mfma_f32_16x16x32_bf16 v[112:115], v[178:181], v[186:189], v[112:115]
	v_mfma_f32_16x16x32_bf16 v[100:103], v[170:173], v[202:205], v[100:103]
	v_mfma_f32_16x16x32_bf16 v[96:99], v[178:181], v[202:205], v[96:99]
	v_mfma_f32_16x16x32_bf16 v[84:87], v[170:173], v[214:217], v[84:87]
	v_mfma_f32_16x16x32_bf16 v[80:83], v[178:181], v[214:217], v[80:83]
	v_mfma_f32_16x16x32_bf16 v[68:71], v[170:173], v[222:225], v[68:71]
	v_mfma_f32_16x16x32_bf16 v[64:67], v[178:181], v[222:225], v[64:67]
	s_setprio 0
	s_barrier
; #define PG8_STAGE(bufoff, gbase, voff) do { _Pragma("unroll") for (int _i = 0; _i < 2; ++_i) \
;         __builtin_amdgcn_global_load_lds((const unsigned*)((const char*)(gbase) + (voff)[_i]), (LAS unsigned*)(lds + (bufoff) + ldsw + _i * 8192), 16, 0, 0); } while (0)
; #define PG8_LDA(dst, b, h) do { _Pragma("unroll") for (int m = 0; m < 4; ++m) _Pragma("unroll") for (int k = 0; k < 2; ++k) dst[m][k] = *(const LAS bf16x8*)(lds + PG8_SA(b, h) + aoff + m * 2048 + k * 1024); } while (0)
; #define PG8_LDB(dst, b, h) do { _Pragma("unroll") for (int n = 0; n < 2; ++n) _Pragma("unroll") for (int k = 0; k < 2; ++k) dst[n][k] = *(const LAS bf16x8*)(lds + PG8_SB(b, h) + boff + n * 2048 + k * 1024); } while (0)
; #define PG8_WAIT_V(n) asm volatile("s_waitcnt vmcnt(" #n ")" ::: "memory")
; #define PG8_BAR __builtin_amdgcn_s_barrier()
; template <class Epi, class Sched>
; __device__ __forceinline__ void gemm_phase(LAS unsigned char* lds, const Gemm g, const Sched& S, const Epi& E) {
;     ...
;         for (int t = 0; t < nt; t += 2) {
;             const bool last = (t == nt - 2);
;             const char* a1 = cA + (size_t)(t + 1) * kstep;
;             const char* a2 = last ? nA : cA + (size_t)(t + 2) * kstep; const char* b2 = last ? nB : cB + (size_t)(t + 2) * kstep;
;             const char* a3 = a2 + kstep; const char* b3 = b2 + kstep;
;             PG8_LDB(B0, 0, 0); PG8_LDB(B1, 0, 1); PG8_SCHED; PG8_LDA(At, 0, 0); PG8_STAGE(PG8_SA(1, 1), a1 + hstepA, voffA);
;             PG8_WAIT_V(8); PG8_WAIT_L(0); PG8_BAR; PG8_MMA(0, 0, At, B0); PG8_MMA(0, 1, At, B1); PG8_BAR; PG8_SCHED;
;             PG8_LDA(At, 0, 1); PG8_STAGE(PG8_SB(0, 0), b2, voffB); PG8_STAGE(PG8_SB(0, 1), b2 + hstepB, voffB); PG8_STAGE(PG8_SA(0, 0), a2, voffA);
;             PG8_WAIT_V(8); PG8_WAIT_L(0); PG8_BAR; PG8_MMA(1, 0, At, B0); PG8_MMA(1, 1, At, B1); PG8_BAR; PG8_SCHED;
;             PG8_LDB(B0, 1, 0); PG8_LDB(B1, 1, 1); PG8_SCHED; PG8_LDA(At, 1, 0); PG8_STAGE(PG8_SA(0, 1), a2 + hstepA, voffA);
;             PG8_WAIT_V(8); PG8_WAIT_L(0); PG8_BAR; PG8_MMA(0, 0, At, B0); PG8_MMA(0, 1, At, B1); PG8_BAR; PG8_SCHED;
;             PG8_LDA(At, 1, 1); PG8_STAGE(PG8_SB(1, 0), b3, voffB); PG8_STAGE(PG8_SB(1, 1), b3 + hstepB, voffB); PG8_STAGE(PG8_SA(1, 0), a3, voffA);
;             PG8_WAIT_V(8); PG8_WAIT_L(0); PG8_BAR; PG8_MMA(1, 0, At, B0); PG8_MMA(1, 1, At, B1); PG8_BAR; PG8_SCHED;
	s_add_i32 s16, s16, s59
	v_lshl_add_u64 v[190:191], v[190:191], 0, s[22:23]
	s_mov_b32 m0, s16
	ds_read_b128 v[182:185], v151 offset:49152
	ds_read_b128 v[186:189], v151 offset:50176
	ds_read_b128 v[198:201], v151 offset:51200
	ds_read_b128 v[202:205], v151 offset:52224
	ds_read_b128 v[210:213], v151 offset:53248
	ds_read_b128 v[214:217], v151 offset:54272
	ds_read_b128 v[218:221], v151 offset:55296
	ds_read_b128 v[222:225], v151 offset:56320
	global_load_lds_dwordx4 v[190:191], off
	s_add_i32 m0, s16, 0x2000
	s_add_u32 s34, s54, 0x20080
	v_lshl_add_u64 v[190:191], v[226:227], 0, s[22:23]
	s_addc_u32 s35, s55, 0
	s_add_i32 s16, s17, s59
	global_load_lds_dwordx4 v[190:191], off
	v_lshl_add_u64 v[190:191], s[34:35], 0, v[128:129]
	s_mov_b32 m0, s16
	s_nop 0
	global_load_lds_dwordx4 v[190:191], off
	v_lshl_add_u64 v[190:191], s[34:35], 0, v[130:131]
	s_add_i32 m0, s16, 0x2000
	s_nop 0
	global_load_lds_dwordx4 v[190:191], off
	v_lshl_add_u64 v[190:191], v[228:229], 0, s[22:23]
	s_mov_b32 m0, s65
	s_nop 0
	global_load_lds_dwordx4 v[190:191], off
	v_lshl_add_u64 v[190:191], v[230:231], 0, s[22:23]
	s_mov_b32 m0, s66
	s_nop 0
	global_load_lds_dwordx4 v[190:191], off
	s_waitcnt vmcnt(8)
	s_waitcnt lgkmcnt(0)
	s_barrier
	s_setprio 1
	s_waitcnt lgkmcnt(0)
	v_mfma_f32_16x16x32_bf16 v[60:63], v[140:143], v[182:185], v[60:63]
	v_mfma_f32_16x16x32_bf16 v[56:59], v[158:161], v[182:185], v[56:59]
	v_mfma_f32_16x16x32_bf16 v[44:47], v[140:143], v[198:201], v[44:47]
	v_mfma_f32_16x16x32_bf16 v[40:43], v[158:161], v[198:201], v[40:43]
	v_mfma_f32_16x16x32_bf16 v[28:31], v[140:143], v[210:213], v[28:31]
	v_mfma_f32_16x16x32_bf16 v[24:27], v[158:161], v[210:213], v[24:27]
	v_mfma_f32_16x16x32_bf16 v[12:15], v[140:143], v[218:221], v[12:15]
	v_mfma_f32_16x16x32_bf16 v[8:11], v[158:161], v[218:221], v[8:11]
	v_mfma_f32_16x16x32_bf16 v[60:63], v[154:157], v[186:189], v[60:63]
	v_mfma_f32_16x16x32_bf16 v[56:59], v[162:165], v[186:189], v[56:59]
	v_mfma_f32_16x16x32_bf16 v[44:47], v[154:157], v[202:205], v[44:47]
	v_mfma_f32_16x16x32_bf16 v[40:43], v[162:165], v[202:205], v[40:43]
	v_mfma_f32_16x16x32_bf16 v[28:31], v[154:157], v[214:217], v[28:31]
	v_mfma_f32_16x16x32_bf16 v[24:27], v[162:165], v[214:217], v[24:27]
	v_mfma_f32_16x16x32_bf16 v[12:15], v[154:157], v[222:225], v[12:15]
	v_mfma_f32_16x16x32_bf16 v[8:11], v[162:165], v[222:225], v[8:11]
	s_setprio 0
	s_setprio 1
	v_mfma_f32_16x16x32_bf16 v[52:55], v[166:169], v[182:185], v[52:55]
	v_mfma_f32_16x16x32_bf16 v[48:51], v[174:177], v[182:185], v[48:51]
	v_mfma_f32_16x16x32_bf16 v[36:39], v[166:169], v[198:201], v[36:39]
	v_mfma_f32_16x16x32_bf16 v[32:35], v[174:177], v[198:201], v[32:35]
	v_mfma_f32_16x16x32_bf16 v[20:23], v[166:169], v[210:213], v[20:23]
	v_mfma_f32_16x16x32_bf16 v[16:19], v[174:177], v[210:213], v[16:19]
	v_mfma_f32_16x16x32_bf16 v[4:7], v[166:169], v[218:221], v[4:7]
	v_mfma_f32_16x16x32_bf16 v[0:3], v[174:177], v[218:221], v[0:3]
	v_mfma_f32_16x16x32_bf16 v[52:55], v[170:173], v[186:189], v[52:55]
	v_mfma_f32_16x16x32_bf16 v[48:51], v[178:181], v[186:189], v[48:51]
	v_mfma_f32_16x16x32_bf16 v[36:39], v[170:173], v[202:205], v[36:39]
	v_mfma_f32_16x16x32_bf16 v[32:35], v[178:181], v[202:205], v[32:35]
	v_mfma_f32_16x16x32_bf16 v[20:23], v[170:173], v[214:217], v[20:23]
	v_mfma_f32_16x16x32_bf16 v[16:19], v[178:181], v[214:217], v[16:19]
	v_mfma_f32_16x16x32_bf16 v[4:7], v[170:173], v[222:225], v[4:7]
	v_mfma_f32_16x16x32_bf16 v[0:3], v[178:181], v[222:225], v[0:3]
	s_setprio 0
	s_add_i32 s73, s73, 2
	s_add_u32 s52, s52, 0x100
	s_addc_u32 s53, s53, 0
	s_add_u32 s71, s71, 0x100
	s_addc_u32 s72, s72, 0
	s_cmp_gt_u32 s73, 5
	s_barrier
	s_cbranch_scc0 .LBB0_725
	s_and_b64 vcc, exec, s[28:29]
	s_cbranch_vccz .LBB0_728
	s_barrier

; #define PG8_STAGE(bufoff, gbase, voff) do { _Pragma("unroll") for (int _i = 0; _i < 2; ++_i) \
;         __builtin_amdgcn_global_load_lds((const unsigned*)((const char*)(gbase) + (voff)[_i]), (LAS unsigned*)(lds + (bufoff) + ldsw + _i * 8192), 16, 0, 0); } while (0)
; #define PG8_LDA(dst, b, h) do { _Pragma("unroll") for (int m = 0; m < 4; ++m) _Pragma("unroll") for (int k = 0; k < 2; ++k) dst[m][k] = *(const LAS bf16x8*)(lds + PG8_SA(b, h) + aoff + m * 2048 + k * 1024); } while (0)
; #define PG8_LDB(dst, b, h) do { _Pragma("unroll") for (int n = 0; n < 2; ++n) _Pragma("unroll") for (int k = 0; k < 2; ++k) dst[n][k] = *(const LAS bf16x8*)(lds + PG8_SB(b, h) + boff + n * 2048 + k * 1024); } while (0)
; #define PG8_MMA(ai, bj, At, Bt) do { __builtin_amdgcn_s_setprio(1); _Pragma("unroll") for (int m = 0; m < 4; ++m) _Pragma("unroll") for (int n = 0; n < 2; ++n) _Pragma("unroll") for (int k = 0; k < 2; ++k) \
;         acc[ai][bj][m][n] = __builtin_amdgcn_mfma_f32_16x16x32_bf16(Bt[n][k], At[m][k], acc[ai][bj][m][n], 0, 0, 0); __builtin_amdgcn_s_setprio(0); } while (0)
; #define PG8_WAIT_V(n) asm volatile("s_waitcnt vmcnt(" #n ")" ::: "memory")
; #define PG8_WAIT_L(n) asm volatile("s_waitcnt lgkmcnt(" #n ")" ::: "memory")
; #define PG8_BAR __builtin_amdgcn_s_barrier()
; #define PG8_SCHED __builtin_amdgcn_sched_barrier(0)
; template <class Epi, class Sched>
; __device__ __forceinline__ void gemm_phase(LAS unsigned char* lds, const Gemm g, const Sched& S, const Epi& E) {
;     ...
;             PG8_LDB(B0, 0, 0); PG8_LDB(B1, 0, 1); PG8_SCHED; PG8_LDA(At, 0, 0); PG8_STAGE(PG8_SA(1, 1), a1 + hstepA, voffA);
;             PG8_WAIT_V(8); PG8_WAIT_L(0); PG8_BAR; PG8_MMA(0, 0, At, B0); PG8_MMA(0, 1, At, B1); PG8_BAR; PG8_SCHED;
;             PG8_LDA(At, 0, 1); PG8_STAGE(PG8_SB(0, 0), b2, voffB); PG8_STAGE(PG8_SB(0, 1), b2 + hstepB, voffB); PG8_STAGE(PG8_SA(0, 0), a2, voffA);
;             PG8_WAIT_V(8); PG8_WAIT_L(0); PG8_BAR; PG8_MMA(1, 0, At, B0); PG8_MMA(1, 1, At, B1); PG8_BAR; PG8_SCHED;
.LBB0_786:
	ds_read_b128 v[40:43], v209
	ds_read_b128 v[44:47], v209 offset:1024
	ds_read_b128 v[48:51], v209 offset:2048
	ds_read_b128 v[52:55], v209 offset:3072
	ds_read_b128 v[64:67], v210
	ds_read_b128 v[68:71], v210 offset:1024
	ds_read_b128 v[72:75], v210 offset:2048
	ds_read_b128 v[76:79], v210 offset:3072
	s_add_u32 s16, s20, 0xfff80080
	s_addc_u32 s17, s21, -1
	s_cmp_eq_u32 s34, 28
	s_cselect_b32 s79, s15, s17
	s_cselect_b32 s78, s19, s16
	s_cselect_b32 s77, s69, vcc_hi
	s_cselect_b32 s76, s71, vcc_lo
	v_lshl_add_u64 v[198:199], s[20:21], 0, v[170:171]
	s_add_i32 m0, s85, 0xc000
	ds_read_b128 v[180:183], v211
	ds_read_b128 v[184:187], v211 offset:1024
	ds_read_b128 v[188:191], v211 offset:2048
	ds_read_b128 v[212:215], v211 offset:3072
	ds_read_b128 v[216:219], v211 offset:4096
	ds_read_b128 v[220:223], v211 offset:5120
	ds_read_b128 v[224:227], v211 offset:6144
	ds_read_b128 v[228:231], v211 offset:7168
	global_load_lds_dwordx4 v[198:199], off
	v_lshl_add_u64 v[198:199], s[20:21], 0, v[172:173]
	s_add_i32 m0, s85, 0xe000
	s_nop 0
	global_load_lds_dwordx4 v[198:199], off
	s_waitcnt vmcnt(8)
	s_waitcnt lgkmcnt(0)
	s_barrier
	s_setprio 1
	s_waitcnt lgkmcnt(0)
	v_mfma_f32_16x16x32_bf16 v[156:159], v[40:43], v[180:183], v[156:159]
	v_mfma_f32_16x16x32_bf16 v[148:151], v[48:51], v[180:183], v[148:151]
	v_mfma_f32_16x16x32_bf16 v[140:143], v[40:43], v[188:191], v[140:143]
	v_mfma_f32_16x16x32_bf16 v[132:135], v[48:51], v[188:191], v[132:135]
	v_mfma_f32_16x16x32_bf16 v[124:127], v[40:43], v[216:219], v[124:127]
	v_mfma_f32_16x16x32_bf16 v[116:119], v[48:51], v[216:219], v[116:119]
	v_mfma_f32_16x16x32_bf16 v[108:111], v[40:43], v[224:227], v[108:111]
	v_mfma_f32_16x16x32_bf16 v[100:103], v[48:51], v[224:227], v[100:103]
	v_mfma_f32_16x16x32_bf16 v[156:159], v[44:47], v[184:187], v[156:159]
	v_mfma_f32_16x16x32_bf16 v[148:151], v[52:55], v[184:187], v[148:151]
	v_mfma_f32_16x16x32_bf16 v[140:143], v[44:47], v[212:215], v[140:143]
	v_mfma_f32_16x16x32_bf16 v[132:135], v[52:55], v[212:215], v[132:135]
	v_mfma_f32_16x16x32_bf16 v[124:127], v[44:47], v[220:223], v[124:127]
	v_mfma_f32_16x16x32_bf16 v[116:119], v[52:55], v[220:223], v[116:119]
	v_mfma_f32_16x16x32_bf16 v[108:111], v[44:47], v[228:231], v[108:111]
	v_mfma_f32_16x16x32_bf16 v[100:103], v[52:55], v[228:231], v[100:103]
	s_setprio 0
	s_setprio 1
	v_mfma_f32_16x16x32_bf16 v[152:155], v[64:67], v[180:183], v[152:155]
	v_mfma_f32_16x16x32_bf16 v[144:147], v[72:75], v[180:183], v[144:147]
	v_mfma_f32_16x16x32_bf16 v[136:139], v[64:67], v[188:191], v[136:139]
	v_mfma_f32_16x16x32_bf16 v[128:131], v[72:75], v[188:191], v[128:131]
	v_mfma_f32_16x16x32_bf16 v[120:123], v[64:67], v[216:219], v[120:123]
	v_mfma_f32_16x16x32_bf16 v[112:115], v[72:75], v[216:219], v[112:115]
	v_mfma_f32_16x16x32_bf16 v[104:107], v[64:67], v[224:227], v[104:107]
	v_mfma_f32_16x16x32_bf16 v[96:99], v[72:75], v[224:227], v[96:99]
	v_mfma_f32_16x16x32_bf16 v[152:155], v[68:71], v[184:187], v[152:155]
	v_mfma_f32_16x16x32_bf16 v[144:147], v[76:79], v[184:187], v[144:147]
	v_mfma_f32_16x16x32_bf16 v[136:139], v[68:71], v[212:215], v[136:139]
	v_mfma_f32_16x16x32_bf16 v[128:131], v[76:79], v[212:215], v[128:131]
	v_mfma_f32_16x16x32_bf16 v[120:123], v[68:71], v[220:223], v[120:123]
	v_mfma_f32_16x16x32_bf16 v[112:115], v[76:79], v[220:223], v[112:115]
	v_mfma_f32_16x16x32_bf16 v[104:107], v[68:71], v[228:231], v[104:107]
	v_mfma_f32_16x16x32_bf16 v[96:99], v[76:79], v[228:231], v[96:99]
	s_setprio 0
	s_barrier
	s_add_i32 s16, s94, s84
	v_lshl_add_u64 v[198:199], s[76:77], 0, v[162:163]
	s_mov_b32 m0, s16
	ds_read_b128 v[180:183], v211 offset:16384
	ds_read_b128 v[184:187], v211 offset:17408
	ds_read_b128 v[188:191], v211 offset:18432
	ds_read_b128 v[212:215], v211 offset:19456
	ds_read_b128 v[216:219], v211 offset:20480
	ds_read_b128 v[220:223], v211 offset:21504
	ds_read_b128 v[224:227], v211 offset:22528
	ds_read_b128 v[228:231], v211 offset:23552
	global_load_lds_dwordx4 v[198:199], off
	s_add_i32 m0, s16, 0x2000
	s_add_u32 s16, s76, 0x80000
	v_lshl_add_u64 v[236:237], s[76:77], 0, v[166:167]
	s_addc_u32 s17, s77, 0
	s_add_i32 s35, s95, s84
	global_load_lds_dwordx4 v[236:237], off
	v_lshl_add_u64 v[232:233], s[16:17], 0, v[162:163]
	s_mov_b32 m0, s35
	v_lshl_add_u64 v[238:239], s[78:79], 0, v[160:161]
	global_load_lds_dwordx4 v[232:233], off
	v_lshl_add_u64 v[232:233], s[16:17], 0, v[166:167]
	s_add_i32 m0, s35, 0x2000
	v_lshl_add_u64 v[240:241], s[78:79], 0, v[164:165]
	global_load_lds_dwordx4 v[232:233], off
	s_mov_b32 m0, s85
	s_nop 0
	global_load_lds_dwordx4 v[238:239], off
	s_mov_b32 m0, s86
	s_nop 0
	global_load_lds_dwordx4 v[240:241], off
	s_waitcnt vmcnt(8)
	s_waitcnt lgkmcnt(0)
	s_barrier
; #define PG8_STAGE(bufoff, gbase, voff) do { _Pragma("unroll") for (int _i = 0; _i < 2; ++_i) \
;         __builtin_amdgcn_global_load_lds((const unsigned*)((const char*)(gbase) + (voff)[_i]), (LAS unsigned*)(lds + (bufoff) + ldsw + _i * 8192), 16, 0, 0); } while (0)
; #define PG8_LDA(dst, b, h) do { _Pragma("unroll") for (int m = 0; m < 4; ++m) _Pragma("unroll") for (int k = 0; k < 2; ++k) dst[m][k] = *(const LAS bf16x8*)(lds + PG8_SA(b, h) + aoff + m * 2048 + k * 1024); } while (0)
; #define PG8_LDB(dst, b, h) do { _Pragma("unroll") for (int n = 0; n < 2; ++n) _Pragma("unroll") for (int k = 0; k < 2; ++k) dst[n][k] = *(const LAS bf16x8*)(lds + PG8_SB(b, h) + boff + n * 2048 + k * 1024); } while (0)
; #define PG8_MMA(ai, bj, At, Bt) do { __builtin_amdgcn_s_setprio(1); _Pragma("unroll") for (int m = 0; m < 4; ++m) _Pragma("unroll") for (int n = 0; n < 2; ++n) _Pragma("unroll") for (int k = 0; k < 2; ++k) \
;         acc[ai][bj][m][n] = __builtin_amdgcn_mfma_f32_16x16x32_bf16(Bt[n][k], At[m][k], acc[ai][bj][m][n], 0, 0, 0); __builtin_amdgcn_s_setprio(0); } while (0)
; #define PG8_WAIT_V(n) asm volatile("s_waitcnt vmcnt(" #n ")" ::: "memory")
; #define PG8_WAIT_L(n) asm volatile("s_waitcnt lgkmcnt(" #n ")" ::: "memory")
; #define PG8_BAR __builtin_amdgcn_s_barrier()
; #define PG8_SCHED __builtin_amdgcn_sched_barrier(0)
; template <class Epi, class Sched>
; __device__ __forceinline__ void gemm_phase(LAS unsigned char* lds, const Gemm g, const Sched& S, const Epi& E) {
;     ...
;             PG8_WAIT_V(8); PG8_WAIT_L(0); PG8_BAR; PG8_MMA(1, 0, At, B0); PG8_MMA(1, 1, At, B1); PG8_BAR; PG8_SCHED;
;             PG8_LDB(B0, 1, 0); PG8_LDB(B1, 1, 1); PG8_SCHED; PG8_LDA(At, 1, 0); PG8_STAGE(PG8_SA(0, 1), a2 + hstepA, voffA);
;             PG8_WAIT_V(8); PG8_WAIT_L(0); PG8_BAR; PG8_MMA(0, 0, At, B0); PG8_MMA(0, 1, At, B1); PG8_BAR; PG8_SCHED;
;             PG8_LDA(At, 1, 1); PG8_STAGE(PG8_SB(1, 0), b3, voffB); PG8_STAGE(PG8_SB(1, 1), b3 + hstepB, voffB); PG8_STAGE(PG8_SA(1, 0), a3, voffA);
	s_setprio 1
	s_waitcnt lgkmcnt(0)
	v_mfma_f32_16x16x32_bf16 v[92:95], v[40:43], v[180:183], v[92:95]
	v_mfma_f32_16x16x32_bf16 v[84:87], v[48:51], v[180:183], v[84:87]
	v_mfma_f32_16x16x32_bf16 v[60:63], v[40:43], v[188:191], v[60:63]
	v_mfma_f32_16x16x32_bf16 v[36:39], v[48:51], v[188:191], v[36:39]
	v_mfma_f32_16x16x32_bf16 v[28:31], v[40:43], v[216:219], v[28:31]
	v_mfma_f32_16x16x32_bf16 v[20:23], v[48:51], v[216:219], v[20:23]
	v_mfma_f32_16x16x32_bf16 v[12:15], v[40:43], v[224:227], v[12:15]
	v_mfma_f32_16x16x32_bf16 v[8:11], v[48:51], v[224:227], v[8:11]
	v_mfma_f32_16x16x32_bf16 v[92:95], v[44:47], v[184:187], v[92:95]
	v_mfma_f32_16x16x32_bf16 v[84:87], v[52:55], v[184:187], v[84:87]
	v_mfma_f32_16x16x32_bf16 v[60:63], v[44:47], v[212:215], v[60:63]
	v_mfma_f32_16x16x32_bf16 v[36:39], v[52:55], v[212:215], v[36:39]
	v_mfma_f32_16x16x32_bf16 v[28:31], v[44:47], v[220:223], v[28:31]
	v_mfma_f32_16x16x32_bf16 v[20:23], v[52:55], v[220:223], v[20:23]
	v_mfma_f32_16x16x32_bf16 v[12:15], v[44:47], v[228:231], v[12:15]
	v_mfma_f32_16x16x32_bf16 v[8:11], v[52:55], v[228:231], v[8:11]
	s_setprio 0
	s_setprio 1
	v_mfma_f32_16x16x32_bf16 v[32:35], v[72:75], v[188:191], v[32:35]
	v_mfma_f32_16x16x32_bf16 v[24:27], v[64:67], v[216:219], v[24:27]
	v_mfma_f32_16x16x32_bf16 v[16:19], v[72:75], v[216:219], v[16:19]
	v_mfma_f32_16x16x32_bf16 v[0:3], v[64:67], v[224:227], v[0:3]
	v_mfma_f32_16x16x32_bf16 v[4:7], v[72:75], v[224:227], v[4:7]
	v_mfma_f32_16x16x32_bf16 v[40:43], v[64:67], v[180:183], v[88:91]
	v_mfma_f32_16x16x32_bf16 v[44:47], v[72:75], v[180:183], v[80:83]
	v_mfma_f32_16x16x32_bf16 v[48:51], v[64:67], v[188:191], v[56:59]
	v_mfma_f32_16x16x32_bf16 v[32:35], v[76:79], v[212:215], v[32:35]
	v_mfma_f32_16x16x32_bf16 v[24:27], v[68:71], v[220:223], v[24:27]
	v_mfma_f32_16x16x32_bf16 v[16:19], v[76:79], v[220:223], v[16:19]
	v_mfma_f32_16x16x32_bf16 v[0:3], v[68:71], v[228:231], v[0:3]
	v_mfma_f32_16x16x32_bf16 v[4:7], v[76:79], v[228:231], v[4:7]
	v_mfma_f32_16x16x32_bf16 v[40:43], v[68:71], v[184:187], v[40:43]
	v_mfma_f32_16x16x32_bf16 v[44:47], v[76:79], v[184:187], v[44:47]
	v_mfma_f32_16x16x32_bf16 v[48:51], v[68:71], v[212:215], v[48:51]
	s_setprio 0
	s_barrier
	s_add_i32 s35, 0, 0x18000
	s_add_i32 s38, 0, 0x1c000
	v_add_u32_e32 v68, s35, v195
	v_add_u32_e32 v80, s38, v195
	ds_read_b128 v[52:55], v68
	ds_read_b128 v[56:59], v68 offset:1024
	ds_read_b128 v[64:67], v68 offset:2048
	ds_read_b128 v[68:71], v68 offset:3072
	ds_read_b128 v[72:75], v80
	ds_read_b128 v[76:79], v80 offset:1024
	ds_read_b128 v[180:183], v80 offset:2048
	ds_read_b128 v[184:187], v80 offset:3072
	s_add_u32 s16, s78, 0x80000
	s_addc_u32 s17, s79, 0
	s_mov_b32 m0, s87
	v_lshl_add_u64 v[232:233], s[16:17], 0, v[160:161]
	ds_read_b128 v[80:83], v211 offset:32768
	ds_read_b128 v[88:91], v211 offset:33792
	ds_read_b128 v[188:191], v211 offset:34816
	ds_read_b128 v[212:215], v211 offset:35840
	ds_read_b128 v[216:219], v211 offset:36864
	ds_read_b128 v[220:223], v211 offset:37888
	ds_read_b128 v[224:227], v211 offset:38912
	ds_read_b128 v[228:231], v211 offset:39936
	global_load_lds_dwordx4 v[232:233], off
	v_lshl_add_u64 v[232:233], s[16:17], 0, v[164:165]
	s_mov_b32 m0, s88
	s_nop 0
	global_load_lds_dwordx4 v[232:233], off
	s_waitcnt vmcnt(8)
	s_waitcnt lgkmcnt(0)
	s_barrier
	s_setprio 1
	s_waitcnt lgkmcnt(0)
	v_mfma_f32_16x16x32_bf16 v[156:159], v[52:55], v[80:83], v[156:159]
	v_mfma_f32_16x16x32_bf16 v[148:151], v[64:67], v[80:83], v[148:151]
	v_mfma_f32_16x16x32_bf16 v[140:143], v[52:55], v[188:191], v[140:143]
	v_mfma_f32_16x16x32_bf16 v[132:135], v[64:67], v[188:191], v[132:135]
	v_mfma_f32_16x16x32_bf16 v[124:127], v[52:55], v[216:219], v[124:127]
	v_mfma_f32_16x16x32_bf16 v[116:119], v[64:67], v[216:219], v[116:119]
	v_mfma_f32_16x16x32_bf16 v[108:111], v[52:55], v[224:227], v[108:111]
	v_mfma_f32_16x16x32_bf16 v[100:103], v[64:67], v[224:227], v[100:103]
	v_mfma_f32_16x16x32_bf16 v[156:159], v[56:59], v[88:91], v[156:159]
	v_mfma_f32_16x16x32_bf16 v[148:151], v[68:71], v[88:91], v[148:151]
	v_mfma_f32_16x16x32_bf16 v[140:143], v[56:59], v[212:215], v[140:143]
	v_mfma_f32_16x16x32_bf16 v[132:135], v[68:71], v[212:215], v[132:135]
	v_mfma_f32_16x16x32_bf16 v[124:127], v[56:59], v[220:223], v[124:127]
	v_mfma_f32_16x16x32_bf16 v[116:119], v[68:71], v[220:223], v[116:119]
	v_mfma_f32_16x16x32_bf16 v[108:111], v[56:59], v[228:231], v[108:111]
	v_mfma_f32_16x16x32_bf16 v[100:103], v[68:71], v[228:231], v[100:103]
	s_setprio 0
	s_setprio 1
	v_mfma_f32_16x16x32_bf16 v[152:155], v[72:75], v[80:83], v[152:155]
	v_mfma_f32_16x16x32_bf16 v[80:83], v[180:183], v[80:83], v[144:147]
	v_mfma_f32_16x16x32_bf16 v[144:147], v[184:187], v[88:91], v[80:83]
	v_mfma_f32_16x16x32_bf16 v[80:83], v[72:75], v[188:191], v[136:139]
	v_mfma_f32_16x16x32_bf16 v[136:139], v[76:79], v[212:215], v[80:83]
	v_mfma_f32_16x16x32_bf16 v[80:83], v[180:183], v[188:191], v[128:131]
	v_mfma_f32_16x16x32_bf16 v[128:131], v[184:187], v[212:215], v[80:83]
	v_mfma_f32_16x16x32_bf16 v[80:83], v[72:75], v[216:219], v[120:123]
	v_mfma_f32_16x16x32_bf16 v[120:123], v[76:79], v[220:223], v[80:83]
	v_mfma_f32_16x16x32_bf16 v[80:83], v[180:183], v[216:219], v[112:115]
	v_mfma_f32_16x16x32_bf16 v[112:115], v[184:187], v[220:223], v[80:83]
	v_mfma_f32_16x16x32_bf16 v[80:83], v[72:75], v[224:227], v[104:107]
	v_mfma_f32_16x16x32_bf16 v[104:107], v[76:79], v[228:231], v[80:83]
	v_mfma_f32_16x16x32_bf16 v[80:83], v[180:183], v[224:227], v[96:99]
	v_mfma_f32_16x16x32_bf16 v[152:155], v[76:79], v[88:91], v[152:155]
	v_mfma_f32_16x16x32_bf16 v[96:99], v[184:187], v[228:231], v[80:83]
	s_setprio 0
	s_barrier
; #define PG8_STAGE(bufoff, gbase, voff) do { _Pragma("unroll") for (int _i = 0; _i < 2; ++_i) \
;         __builtin_amdgcn_global_load_lds((const unsigned*)((const char*)(gbase) + (voff)[_i]), (LAS unsigned*)(lds + (bufoff) + ldsw + _i * 8192), 16, 0, 0); } while (0)
; #define PG8_LDA(dst, b, h) do { _Pragma("unroll") for (int m = 0; m < 4; ++m) _Pragma("unroll") for (int k = 0; k < 2; ++k) dst[m][k] = *(const LAS bf16x8*)(lds + PG8_SA(b, h) + aoff + m * 2048 + k * 1024); } while (0)
; #define PG8_LDB(dst, b, h) do { _Pragma("unroll") for (int n = 0; n < 2; ++n) _Pragma("unroll") for (int k = 0; k < 2; ++k) dst[n][k] = *(const LAS bf16x8*)(lds + PG8_SB(b, h) + boff + n * 2048 + k * 1024); } while (0)
; #define PG8_WAIT_V(n) asm volatile("s_waitcnt vmcnt(" #n ")" ::: "memory")
; #define PG8_BAR __builtin_amdgcn_s_barrier()
; template <class Epi, class Sched>
; __device__ __forceinline__ void gemm_phase(LAS unsigned char* lds, const Gemm g, const Sched& S, const Epi& E) {
;     ...
;         for (int t = 0; t < nt; t += 2) {
;             const bool last = (t == nt - 2);
;             const char* a1 = cA + (size_t)(t + 1) * kstep;
;             const char* a2 = last ? nA : cA + (size_t)(t + 2) * kstep; const char* b2 = last ? nB : cB + (size_t)(t + 2) * kstep;
;             const char* a3 = a2 + kstep; const char* b3 = b2 + kstep;
;             PG8_LDB(B0, 0, 0); PG8_LDB(B1, 0, 1); PG8_SCHED; PG8_LDA(At, 0, 0); PG8_STAGE(PG8_SA(1, 1), a1 + hstepA, voffA);
;             PG8_WAIT_V(8); PG8_WAIT_L(0); PG8_BAR; PG8_MMA(0, 0, At, B0); PG8_MMA(0, 1, At, B1); PG8_BAR; PG8_SCHED;
;             PG8_LDA(At, 0, 1); PG8_STAGE(PG8_SB(0, 0), b2, voffB); PG8_STAGE(PG8_SB(0, 1), b2 + hstepB, voffB); PG8_STAGE(PG8_SA(0, 0), a2, voffA);
;             PG8_WAIT_V(8); PG8_WAIT_L(0); PG8_BAR; PG8_MMA(1, 0, At, B0); PG8_MMA(1, 1, At, B1); PG8_BAR; PG8_SCHED;
;             PG8_LDB(B0, 1, 0); PG8_LDB(B1, 1, 1); PG8_SCHED; PG8_LDA(At, 1, 0); PG8_STAGE(PG8_SA(0, 1), a2 + hstepA, voffA);
;             PG8_WAIT_V(8); PG8_WAIT_L(0); PG8_BAR; PG8_MMA(0, 0, At, B0); PG8_MMA(0, 1, At, B1); PG8_BAR; PG8_SCHED;
;             PG8_LDA(At, 1, 1); PG8_STAGE(PG8_SB(1, 0), b3, voffB); PG8_STAGE(PG8_SB(1, 1), b3 + hstepB, voffB); PG8_STAGE(PG8_SA(1, 0), a3, voffA);
;             PG8_WAIT_V(8); PG8_WAIT_L(0); PG8_BAR; PG8_MMA(1, 0, At, B0); PG8_MMA(1, 1, At, B1); PG8_BAR; PG8_SCHED;
	s_add_i32 s16, s35, s84
	v_lshl_add_u64 v[88:89], v[198:199], 0, s[54:55]
	s_mov_b32 m0, s16
	s_nop 0
	ds_read_b128 v[80:83], v211 offset:49152
	ds_read_b128 v[188:191], v211 offset:50176
	ds_read_b128 v[212:215], v211 offset:51200
	ds_read_b128 v[216:219], v211 offset:52224
	ds_read_b128 v[220:223], v211 offset:53248
	ds_read_b128 v[224:227], v211 offset:54272
	ds_read_b128 v[228:231], v211 offset:55296
	ds_read_b128 v[232:235], v211 offset:56320
	global_load_lds_dwordx4 v[88:89], off
	s_add_i32 m0, s16, 0x2000
	s_add_u32 s16, s76, 0x80080
	v_lshl_add_u64 v[88:89], v[236:237], 0, s[54:55]
	s_addc_u32 s17, s77, 0
	s_add_i32 s35, s38, s84
	global_load_lds_dwordx4 v[88:89], off
	v_lshl_add_u64 v[88:89], s[16:17], 0, v[162:163]
	s_mov_b32 m0, s35
	s_nop 0
	global_load_lds_dwordx4 v[88:89], off
	v_lshl_add_u64 v[88:89], s[16:17], 0, v[166:167]
	s_add_i32 m0, s35, 0x2000
	s_nop 0
	global_load_lds_dwordx4 v[88:89], off
	v_lshl_add_u64 v[88:89], v[238:239], 0, s[54:55]
	s_mov_b32 m0, s90
	s_nop 0
	global_load_lds_dwordx4 v[88:89], off
	v_lshl_add_u64 v[88:89], v[240:241], 0, s[54:55]
	s_mov_b32 m0, s91
	s_nop 0
	global_load_lds_dwordx4 v[88:89], off
	s_waitcnt vmcnt(8)
	s_waitcnt lgkmcnt(0)
	s_barrier
	s_setprio 1
	s_waitcnt lgkmcnt(0)
	v_mfma_f32_16x16x32_bf16 v[88:91], v[52:55], v[80:83], v[92:95]
	v_mfma_f32_16x16x32_bf16 v[84:87], v[64:67], v[80:83], v[84:87]
	v_mfma_f32_16x16x32_bf16 v[60:63], v[52:55], v[212:215], v[60:63]
	v_mfma_f32_16x16x32_bf16 v[36:39], v[64:67], v[212:215], v[36:39]
	v_mfma_f32_16x16x32_bf16 v[28:31], v[52:55], v[220:223], v[28:31]
	v_mfma_f32_16x16x32_bf16 v[20:23], v[64:67], v[220:223], v[20:23]
	v_mfma_f32_16x16x32_bf16 v[12:15], v[52:55], v[228:231], v[12:15]
	v_mfma_f32_16x16x32_bf16 v[8:11], v[64:67], v[228:231], v[8:11]
	v_mfma_f32_16x16x32_bf16 v[92:95], v[56:59], v[188:191], v[88:91]
	v_mfma_f32_16x16x32_bf16 v[84:87], v[68:71], v[188:191], v[84:87]
	v_mfma_f32_16x16x32_bf16 v[60:63], v[56:59], v[216:219], v[60:63]
	v_mfma_f32_16x16x32_bf16 v[36:39], v[68:71], v[216:219], v[36:39]
	v_mfma_f32_16x16x32_bf16 v[28:31], v[56:59], v[224:227], v[28:31]
	v_mfma_f32_16x16x32_bf16 v[20:23], v[68:71], v[224:227], v[20:23]
	v_mfma_f32_16x16x32_bf16 v[12:15], v[56:59], v[232:235], v[12:15]
	v_mfma_f32_16x16x32_bf16 v[8:11], v[68:71], v[232:235], v[8:11]
	s_setprio 0
	s_setprio 1
	v_mfma_f32_16x16x32_bf16 v[40:43], v[72:75], v[80:83], v[40:43]
	v_mfma_f32_16x16x32_bf16 v[88:91], v[76:79], v[188:191], v[40:43]
	v_mfma_f32_16x16x32_bf16 v[40:43], v[180:183], v[80:83], v[44:47]
	v_mfma_f32_16x16x32_bf16 v[80:83], v[184:187], v[188:191], v[40:43]
	v_mfma_f32_16x16x32_bf16 v[40:43], v[72:75], v[212:215], v[48:51]
	v_mfma_f32_16x16x32_bf16 v[32:35], v[180:183], v[212:215], v[32:35]
	v_mfma_f32_16x16x32_bf16 v[24:27], v[72:75], v[220:223], v[24:27]
	v_mfma_f32_16x16x32_bf16 v[16:19], v[180:183], v[220:223], v[16:19]
	v_mfma_f32_16x16x32_bf16 v[0:3], v[72:75], v[228:231], v[0:3]
	v_mfma_f32_16x16x32_bf16 v[4:7], v[180:183], v[228:231], v[4:7]
	v_mfma_f32_16x16x32_bf16 v[56:59], v[76:79], v[216:219], v[40:43]
	v_mfma_f32_16x16x32_bf16 v[32:35], v[184:187], v[216:219], v[32:35]
	v_mfma_f32_16x16x32_bf16 v[24:27], v[76:79], v[224:227], v[24:27]
	v_mfma_f32_16x16x32_bf16 v[16:19], v[184:187], v[224:227], v[16:19]
	v_mfma_f32_16x16x32_bf16 v[0:3], v[76:79], v[232:235], v[0:3]
	v_mfma_f32_16x16x32_bf16 v[4:7], v[184:187], v[232:235], v[4:7]
	s_setprio 0
	s_add_i32 s34, s34, 2
	s_add_u32 s20, s20, 0x100
	s_addc_u32 s21, s21, 0
	s_add_u32 vcc_lo, vcc_lo, 0x100
	s_addc_u32 vcc_hi, vcc_hi, 0
	s_cmp_gt_u32 s34, 29
	s_barrier
	s_cbranch_scc0 .LBB0_786
	s_and_b64 vcc, exec, s[56:57]
	s_cbranch_vccz .LBB0_789
	s_barrier

; #define PG8_STAGE(bufoff, gbase, voff) do { _Pragma("unroll") for (int _i = 0; _i < 2; ++_i) \
;         __builtin_amdgcn_global_load_lds((const unsigned*)((const char*)(gbase) + (voff)[_i]), (LAS unsigned*)(lds + (bufoff) + ldsw + _i * 8192), 16, 0, 0); } while (0)
; #define PG8_LDA(dst, b, h) do { _Pragma("unroll") for (int m = 0; m < 4; ++m) _Pragma("unroll") for (int k = 0; k < 2; ++k) dst[m][k] = *(const LAS bf16x8*)(lds + PG8_SA(b, h) + aoff + m * 2048 + k * 1024); } while (0)
; #define PG8_LDB(dst, b, h) do { _Pragma("unroll") for (int n = 0; n < 2; ++n) _Pragma("unroll") for (int k = 0; k < 2; ++k) dst[n][k] = *(const LAS bf16x8*)(lds + PG8_SB(b, h) + boff + n * 2048 + k * 1024); } while (0)
; #define PG8_MMA(ai, bj, At, Bt) do { __builtin_amdgcn_s_setprio(1); _Pragma("unroll") for (int m = 0; m < 4; ++m) _Pragma("unroll") for (int n = 0; n < 2; ++n) _Pragma("unroll") for (int k = 0; k < 2; ++k) \
;         acc[ai][bj][m][n] = __builtin_amdgcn_mfma_f32_16x16x32_bf16(Bt[n][k], At[m][k], acc[ai][bj][m][n], 0, 0, 0); __builtin_amdgcn_s_setprio(0); } while (0)
; #define PG8_WAIT_V(n) asm volatile("s_waitcnt vmcnt(" #n ")" ::: "memory")
; #define PG8_WAIT_L(n) asm volatile("s_waitcnt lgkmcnt(" #n ")" ::: "memory")
; #define PG8_BAR __builtin_amdgcn_s_barrier()
; #define PG8_SCHED __builtin_amdgcn_sched_barrier(0)
; template <class Epi, class Sched>
; __device__ __forceinline__ void gemm_phase(LAS unsigned char* lds, const Gemm g, const Sched& S, const Epi& E) {
;     ...
;             PG8_LDB(B0, 0, 0); PG8_LDB(B1, 0, 1); PG8_SCHED; PG8_LDA(At, 0, 0); PG8_STAGE(PG8_SA(1, 1), a1 + hstepA, voffA);
;             PG8_WAIT_V(8); PG8_WAIT_L(0); PG8_BAR; PG8_MMA(0, 0, At, B0); PG8_MMA(0, 1, At, B1); PG8_BAR; PG8_SCHED;
;             PG8_LDA(At, 0, 1); PG8_STAGE(PG8_SB(0, 0), b2, voffB); PG8_STAGE(PG8_SB(0, 1), b2 + hstepB, voffB); PG8_STAGE(PG8_SA(0, 0), a2, voffA);
;             PG8_WAIT_V(8); PG8_WAIT_L(0); PG8_BAR; PG8_MMA(1, 0, At, B0); PG8_MMA(1, 1, At, B1); PG8_BAR; PG8_SCHED;
.LBB0_898:
	ds_read_b128 v[140:143], v147
	ds_read_b128 v[150:153], v147 offset:1024
	ds_read_b128 v[154:157], v147 offset:2048
	ds_read_b128 v[158:161], v147 offset:3072
	ds_read_b128 v[162:165], v148
	ds_read_b128 v[166:169], v148 offset:1024
	ds_read_b128 v[170:173], v148 offset:2048
	ds_read_b128 v[174:177], v148 offset:3072
	s_add_u32 s28, s26, 0xffea0080
	s_addc_u32 s29, s27, -1
	s_cmpk_eq_i32 s60, 0x54
	s_cselect_b32 s31, s5, s29
	s_cselect_b32 s30, s4, s28
	s_cselect_b32 s29, s25, s59
	s_cselect_b32 s28, s24, s58
	v_lshl_add_u64 v[210:211], s[26:27], 0, v[132:133]
	s_add_i32 m0, s38, 0xc000
	ds_read_b128 v[178:181], v149
	ds_read_b128 v[182:185], v149 offset:1024
	ds_read_b128 v[186:189], v149 offset:2048
	ds_read_b128 v[190:193], v149 offset:3072
	ds_read_b128 v[194:197], v149 offset:4096
	ds_read_b128 v[198:201], v149 offset:5120
	ds_read_b128 v[202:205], v149 offset:6144
	ds_read_b128 v[206:209], v149 offset:7168
	global_load_lds_dwordx4 v[210:211], off
	v_lshl_add_u64 v[210:211], s[26:27], 0, v[134:135]
	s_add_i32 m0, s38, 0xe000
	s_nop 0
	global_load_lds_dwordx4 v[210:211], off
	s_waitcnt vmcnt(8)
	s_waitcnt lgkmcnt(0)
	s_barrier
	s_setprio 1
	s_waitcnt lgkmcnt(0)
	v_mfma_f32_16x16x32_bf16 v[124:127], v[140:143], v[178:181], v[124:127]
	v_mfma_f32_16x16x32_bf16 v[120:123], v[154:157], v[178:181], v[120:123]
	v_mfma_f32_16x16x32_bf16 v[108:111], v[140:143], v[186:189], v[108:111]
	v_mfma_f32_16x16x32_bf16 v[104:107], v[154:157], v[186:189], v[104:107]
	v_mfma_f32_16x16x32_bf16 v[92:95], v[140:143], v[194:197], v[92:95]
	v_mfma_f32_16x16x32_bf16 v[88:91], v[154:157], v[194:197], v[88:91]
	v_mfma_f32_16x16x32_bf16 v[76:79], v[140:143], v[202:205], v[76:79]
	v_mfma_f32_16x16x32_bf16 v[72:75], v[154:157], v[202:205], v[72:75]
	v_mfma_f32_16x16x32_bf16 v[124:127], v[150:153], v[182:185], v[124:127]
	v_mfma_f32_16x16x32_bf16 v[120:123], v[158:161], v[182:185], v[120:123]
	v_mfma_f32_16x16x32_bf16 v[108:111], v[150:153], v[190:193], v[108:111]
	v_mfma_f32_16x16x32_bf16 v[104:107], v[158:161], v[190:193], v[104:107]
	v_mfma_f32_16x16x32_bf16 v[92:95], v[150:153], v[198:201], v[92:95]
	v_mfma_f32_16x16x32_bf16 v[88:91], v[158:161], v[198:201], v[88:91]
	v_mfma_f32_16x16x32_bf16 v[76:79], v[150:153], v[206:209], v[76:79]
	v_mfma_f32_16x16x32_bf16 v[72:75], v[158:161], v[206:209], v[72:75]
	s_setprio 0
	s_setprio 1
	v_mfma_f32_16x16x32_bf16 v[116:119], v[162:165], v[178:181], v[116:119]
	v_mfma_f32_16x16x32_bf16 v[112:115], v[170:173], v[178:181], v[112:115]
	v_mfma_f32_16x16x32_bf16 v[100:103], v[162:165], v[186:189], v[100:103]
	v_mfma_f32_16x16x32_bf16 v[96:99], v[170:173], v[186:189], v[96:99]
	v_mfma_f32_16x16x32_bf16 v[84:87], v[162:165], v[194:197], v[84:87]
	v_mfma_f32_16x16x32_bf16 v[80:83], v[170:173], v[194:197], v[80:83]
	v_mfma_f32_16x16x32_bf16 v[68:71], v[162:165], v[202:205], v[68:71]
	v_mfma_f32_16x16x32_bf16 v[64:67], v[170:173], v[202:205], v[64:67]
	v_mfma_f32_16x16x32_bf16 v[116:119], v[166:169], v[182:185], v[116:119]
	v_mfma_f32_16x16x32_bf16 v[112:115], v[174:177], v[182:185], v[112:115]
	v_mfma_f32_16x16x32_bf16 v[100:103], v[166:169], v[190:193], v[100:103]
	v_mfma_f32_16x16x32_bf16 v[96:99], v[174:177], v[190:193], v[96:99]
	v_mfma_f32_16x16x32_bf16 v[84:87], v[166:169], v[198:201], v[84:87]
	v_mfma_f32_16x16x32_bf16 v[80:83], v[174:177], v[198:201], v[80:83]
	v_mfma_f32_16x16x32_bf16 v[68:71], v[166:169], v[206:209], v[68:71]
	v_mfma_f32_16x16x32_bf16 v[64:67], v[174:177], v[206:209], v[64:67]
	s_setprio 0
	s_barrier
	s_add_i32 s61, s48, s37
	v_lshl_add_u64 v[210:211], s[28:29], 0, v[128:129]
	s_mov_b32 m0, s61
	ds_read_b128 v[178:181], v149 offset:16384
	ds_read_b128 v[182:185], v149 offset:17408
	ds_read_b128 v[186:189], v149 offset:18432
	ds_read_b128 v[190:193], v149 offset:19456
	ds_read_b128 v[194:197], v149 offset:20480
	ds_read_b128 v[198:201], v149 offset:21504
	ds_read_b128 v[202:205], v149 offset:22528
	ds_read_b128 v[206:209], v149 offset:23552
	global_load_lds_dwordx4 v[210:211], off
	s_add_i32 m0, s61, 0x2000
	s_add_u32 s62, s28, 0x160000
	v_lshl_add_u64 v[212:213], s[28:29], 0, v[130:131]
	s_addc_u32 s63, s29, 0
	s_add_i32 s61, s49, s37
	global_load_lds_dwordx4 v[212:213], off
	v_lshl_add_u64 v[214:215], s[62:63], 0, v[128:129]
	s_mov_b32 m0, s61
	v_lshl_add_u64 v[216:217], s[30:31], 0, v[130:131]
	global_load_lds_dwordx4 v[214:215], off
	v_lshl_add_u64 v[214:215], s[62:63], 0, v[130:131]
	s_add_i32 m0, s61, 0x2000
	s_nop 0
	global_load_lds_dwordx4 v[214:215], off
	v_lshl_add_u64 v[214:215], s[30:31], 0, v[128:129]
	s_mov_b32 m0, s38
	s_nop 0
	global_load_lds_dwordx4 v[214:215], off
	s_mov_b32 m0, s39
	s_nop 0
	global_load_lds_dwordx4 v[216:217], off
	s_waitcnt vmcnt(8)
	s_waitcnt lgkmcnt(0)
	s_barrier
; #define PG8_STAGE(bufoff, gbase, voff) do { _Pragma("unroll") for (int _i = 0; _i < 2; ++_i) \
;         __builtin_amdgcn_global_load_lds((const unsigned*)((const char*)(gbase) + (voff)[_i]), (LAS unsigned*)(lds + (bufoff) + ldsw + _i * 8192), 16, 0, 0); } while (0)
; #define PG8_LDA(dst, b, h) do { _Pragma("unroll") for (int m = 0; m < 4; ++m) _Pragma("unroll") for (int k = 0; k < 2; ++k) dst[m][k] = *(const LAS bf16x8*)(lds + PG8_SA(b, h) + aoff + m * 2048 + k * 1024); } while (0)
; #define PG8_LDB(dst, b, h) do { _Pragma("unroll") for (int n = 0; n < 2; ++n) _Pragma("unroll") for (int k = 0; k < 2; ++k) dst[n][k] = *(const LAS bf16x8*)(lds + PG8_SB(b, h) + boff + n * 2048 + k * 1024); } while (0)
; #define PG8_MMA(ai, bj, At, Bt) do { __builtin_amdgcn_s_setprio(1); _Pragma("unroll") for (int m = 0; m < 4; ++m) _Pragma("unroll") for (int n = 0; n < 2; ++n) _Pragma("unroll") for (int k = 0; k < 2; ++k) \
;         acc[ai][bj][m][n] = __builtin_amdgcn_mfma_f32_16x16x32_bf16(Bt[n][k], At[m][k], acc[ai][bj][m][n], 0, 0, 0); __builtin_amdgcn_s_setprio(0); } while (0)
; #define PG8_WAIT_V(n) asm volatile("s_waitcnt vmcnt(" #n ")" ::: "memory")
; #define PG8_WAIT_L(n) asm volatile("s_waitcnt lgkmcnt(" #n ")" ::: "memory")
; #define PG8_BAR __builtin_amdgcn_s_barrier()
; #define PG8_SCHED __builtin_amdgcn_sched_barrier(0)
; template <class Epi, class Sched>
; __device__ __forceinline__ void gemm_phase(LAS unsigned char* lds, const Gemm g, const Sched& S, const Epi& E) {
;     ...
;             PG8_WAIT_V(8); PG8_WAIT_L(0); PG8_BAR; PG8_MMA(1, 0, At, B0); PG8_MMA(1, 1, At, B1); PG8_BAR; PG8_SCHED;
;             PG8_LDB(B0, 1, 0); PG8_LDB(B1, 1, 1); PG8_SCHED; PG8_LDA(At, 1, 0); PG8_STAGE(PG8_SA(0, 1), a2 + hstepA, voffA);
;             PG8_WAIT_V(8); PG8_WAIT_L(0); PG8_BAR; PG8_MMA(0, 0, At, B0); PG8_MMA(0, 1, At, B1); PG8_BAR; PG8_SCHED;
	s_setprio 1
	s_waitcnt lgkmcnt(0)
	v_mfma_f32_16x16x32_bf16 v[60:63], v[140:143], v[178:181], v[60:63]
	v_mfma_f32_16x16x32_bf16 v[56:59], v[154:157], v[178:181], v[56:59]
	v_mfma_f32_16x16x32_bf16 v[44:47], v[140:143], v[186:189], v[44:47]
	v_mfma_f32_16x16x32_bf16 v[40:43], v[154:157], v[186:189], v[40:43]
	v_mfma_f32_16x16x32_bf16 v[28:31], v[140:143], v[194:197], v[28:31]
	v_mfma_f32_16x16x32_bf16 v[24:27], v[154:157], v[194:197], v[24:27]
	v_mfma_f32_16x16x32_bf16 v[12:15], v[140:143], v[202:205], v[12:15]
	v_mfma_f32_16x16x32_bf16 v[8:11], v[154:157], v[202:205], v[8:11]
	v_mfma_f32_16x16x32_bf16 v[60:63], v[150:153], v[182:185], v[60:63]
	v_mfma_f32_16x16x32_bf16 v[56:59], v[158:161], v[182:185], v[56:59]
	v_mfma_f32_16x16x32_bf16 v[44:47], v[150:153], v[190:193], v[44:47]
	v_mfma_f32_16x16x32_bf16 v[40:43], v[158:161], v[190:193], v[40:43]
	v_mfma_f32_16x16x32_bf16 v[28:31], v[150:153], v[198:201], v[28:31]
	v_mfma_f32_16x16x32_bf16 v[24:27], v[158:161], v[198:201], v[24:27]
	v_mfma_f32_16x16x32_bf16 v[12:15], v[150:153], v[206:209], v[12:15]
	v_mfma_f32_16x16x32_bf16 v[8:11], v[158:161], v[206:209], v[8:11]
	s_setprio 0
	s_setprio 1
	v_mfma_f32_16x16x32_bf16 v[52:55], v[162:165], v[178:181], v[52:55]
	v_mfma_f32_16x16x32_bf16 v[48:51], v[170:173], v[178:181], v[48:51]
	v_mfma_f32_16x16x32_bf16 v[36:39], v[162:165], v[186:189], v[36:39]
	v_mfma_f32_16x16x32_bf16 v[32:35], v[170:173], v[186:189], v[32:35]
	v_mfma_f32_16x16x32_bf16 v[20:23], v[162:165], v[194:197], v[20:23]
	v_mfma_f32_16x16x32_bf16 v[16:19], v[170:173], v[194:197], v[16:19]
	v_mfma_f32_16x16x32_bf16 v[4:7], v[162:165], v[202:205], v[4:7]
	v_mfma_f32_16x16x32_bf16 v[0:3], v[170:173], v[202:205], v[0:3]
	v_mfma_f32_16x16x32_bf16 v[52:55], v[166:169], v[182:185], v[52:55]
	v_mfma_f32_16x16x32_bf16 v[48:51], v[174:177], v[182:185], v[48:51]
	v_mfma_f32_16x16x32_bf16 v[36:39], v[166:169], v[190:193], v[36:39]
	v_mfma_f32_16x16x32_bf16 v[32:35], v[174:177], v[190:193], v[32:35]
	v_mfma_f32_16x16x32_bf16 v[20:23], v[166:169], v[198:201], v[20:23]
	v_mfma_f32_16x16x32_bf16 v[16:19], v[174:177], v[198:201], v[16:19]
	v_mfma_f32_16x16x32_bf16 v[4:7], v[166:169], v[206:209], v[4:7]
	v_mfma_f32_16x16x32_bf16 v[0:3], v[174:177], v[206:209], v[0:3]
	s_setprio 0
	s_barrier
	s_add_i32 s61, 0, 0x18000
	s_add_i32 s62, 0, 0x1c000
	v_add_u32_e32 v158, s61, v145
	v_add_u32_e32 v174, s62, v145
	ds_read_b128 v[140:143], v158
	ds_read_b128 v[150:153], v158 offset:1024
	ds_read_b128 v[154:157], v158 offset:2048
	ds_read_b128 v[158:161], v158 offset:3072
	ds_read_b128 v[162:165], v174
	ds_read_b128 v[166:169], v174 offset:1024
	ds_read_b128 v[170:173], v174 offset:2048
	ds_read_b128 v[174:177], v174 offset:3072
	s_add_u32 s30, s30, 0x160000
	s_addc_u32 s31, s31, 0
	s_mov_b32 m0, s40
	v_lshl_add_u64 v[218:219], s[30:31], 0, v[128:129]
	ds_read_b128 v[178:181], v149 offset:32768
	ds_read_b128 v[182:185], v149 offset:33792
	ds_read_b128 v[186:189], v149 offset:34816
	ds_read_b128 v[190:193], v149 offset:35840
	ds_read_b128 v[194:197], v149 offset:36864
	ds_read_b128 v[198:201], v149 offset:37888
	ds_read_b128 v[202:205], v149 offset:38912
	ds_read_b128 v[206:209], v149 offset:39936
	global_load_lds_dwordx4 v[218:219], off
	v_lshl_add_u64 v[218:219], s[30:31], 0, v[130:131]
	s_mov_b32 m0, s41
	s_nop 0
	global_load_lds_dwordx4 v[218:219], off
	s_waitcnt vmcnt(8)
	s_waitcnt lgkmcnt(0)
	s_barrier
	s_setprio 1
	s_waitcnt lgkmcnt(0)
	v_mfma_f32_16x16x32_bf16 v[124:127], v[140:143], v[178:181], v[124:127]
	v_mfma_f32_16x16x32_bf16 v[120:123], v[154:157], v[178:181], v[120:123]
	v_mfma_f32_16x16x32_bf16 v[108:111], v[140:143], v[186:189], v[108:111]
	v_mfma_f32_16x16x32_bf16 v[104:107], v[154:157], v[186:189], v[104:107]
	v_mfma_f32_16x16x32_bf16 v[92:95], v[140:143], v[194:197], v[92:95]
	v_mfma_f32_16x16x32_bf16 v[88:91], v[154:157], v[194:197], v[88:91]
	v_mfma_f32_16x16x32_bf16 v[76:79], v[140:143], v[202:205], v[76:79]
	v_mfma_f32_16x16x32_bf16 v[72:75], v[154:157], v[202:205], v[72:75]
	v_mfma_f32_16x16x32_bf16 v[124:127], v[150:153], v[182:185], v[124:127]
	v_mfma_f32_16x16x32_bf16 v[120:123], v[158:161], v[182:185], v[120:123]
	v_mfma_f32_16x16x32_bf16 v[108:111], v[150:153], v[190:193], v[108:111]
	v_mfma_f32_16x16x32_bf16 v[104:107], v[158:161], v[190:193], v[104:107]
	v_mfma_f32_16x16x32_bf16 v[92:95], v[150:153], v[198:201], v[92:95]
	v_mfma_f32_16x16x32_bf16 v[88:91], v[158:161], v[198:201], v[88:91]
	v_mfma_f32_16x16x32_bf16 v[76:79], v[150:153], v[206:209], v[76:79]
	v_mfma_f32_16x16x32_bf16 v[72:75], v[158:161], v[206:209], v[72:75]
	s_setprio 0
	s_setprio 1
	v_mfma_f32_16x16x32_bf16 v[116:119], v[162:165], v[178:181], v[116:119]
	v_mfma_f32_16x16x32_bf16 v[112:115], v[170:173], v[178:181], v[112:115]
	v_mfma_f32_16x16x32_bf16 v[100:103], v[162:165], v[186:189], v[100:103]
	v_mfma_f32_16x16x32_bf16 v[96:99], v[170:173], v[186:189], v[96:99]
	v_mfma_f32_16x16x32_bf16 v[84:87], v[162:165], v[194:197], v[84:87]
	v_mfma_f32_16x16x32_bf16 v[80:83], v[170:173], v[194:197], v[80:83]
	v_mfma_f32_16x16x32_bf16 v[68:71], v[162:165], v[202:205], v[68:71]
	v_mfma_f32_16x16x32_bf16 v[64:67], v[170:173], v[202:205], v[64:67]
	v_mfma_f32_16x16x32_bf16 v[116:119], v[166:169], v[182:185], v[116:119]
	v_mfma_f32_16x16x32_bf16 v[112:115], v[174:177], v[182:185], v[112:115]
	v_mfma_f32_16x16x32_bf16 v[100:103], v[166:169], v[190:193], v[100:103]
	v_mfma_f32_16x16x32_bf16 v[96:99], v[174:177], v[190:193], v[96:99]
	v_mfma_f32_16x16x32_bf16 v[84:87], v[166:169], v[198:201], v[84:87]
	v_mfma_f32_16x16x32_bf16 v[80:83], v[174:177], v[198:201], v[80:83]
	v_mfma_f32_16x16x32_bf16 v[68:71], v[166:169], v[206:209], v[68:71]
	v_mfma_f32_16x16x32_bf16 v[64:67], v[174:177], v[206:209], v[64:67]
	s_setprio 0
	s_barrier
; #define PG8_STAGE(bufoff, gbase, voff) do { _Pragma("unroll") for (int _i = 0; _i < 2; ++_i) \
;         __builtin_amdgcn_global_load_lds((const unsigned*)((const char*)(gbase) + (voff)[_i]), (LAS unsigned*)(lds + (bufoff) + ldsw + _i * 8192), 16, 0, 0); } while (0)
; #define PG8_LDA(dst, b, h) do { _Pragma("unroll") for (int m = 0; m < 4; ++m) _Pragma("unroll") for (int k = 0; k < 2; ++k) dst[m][k] = *(const LAS bf16x8*)(lds + PG8_SA(b, h) + aoff + m * 2048 + k * 1024); } while (0)
; #define PG8_MMA(ai, bj, At, Bt) do { __builtin_amdgcn_s_setprio(1); _Pragma("unroll") for (int m = 0; m < 4; ++m) _Pragma("unroll") for (int n = 0; n < 2; ++n) _Pragma("unroll") for (int k = 0; k < 2; ++k) \
;         acc[ai][bj][m][n] = __builtin_amdgcn_mfma_f32_16x16x32_bf16(Bt[n][k], At[m][k], acc[ai][bj][m][n], 0, 0, 0); __builtin_amdgcn_s_setprio(0); } while (0)
; #define PG8_WAIT_V(n) asm volatile("s_waitcnt vmcnt(" #n ")" ::: "memory")
; #define PG8_WAIT_L(n) asm volatile("s_waitcnt lgkmcnt(" #n ")" ::: "memory")
; #define PG8_BAR __builtin_amdgcn_s_barrier()
; #define PG8_SCHED __builtin_amdgcn_sched_barrier(0)
; template <class Epi, class Sched>
; __device__ __forceinline__ void gemm_phase(LAS unsigned char* lds, const Gemm g, const Sched& S, const Epi& E) {
;     ...
;             PG8_LDA(At, 1, 1); PG8_STAGE(PG8_SB(1, 0), b3, voffB); PG8_STAGE(PG8_SB(1, 1), b3 + hstepB, voffB); PG8_STAGE(PG8_SA(1, 0), a3, voffA);
;             PG8_WAIT_V(8); PG8_WAIT_L(0); PG8_BAR; PG8_MMA(1, 0, At, B0); PG8_MMA(1, 1, At, B1); PG8_BAR; PG8_SCHED;
;         }
;         if (wr == 0) PG8_BAR;
	s_add_i32 s30, s61, s37
	v_lshl_add_u64 v[210:211], v[210:211], 0, s[14:15]
	s_mov_b32 m0, s30
	ds_read_b128 v[178:181], v149 offset:49152
	ds_read_b128 v[182:185], v149 offset:50176
	ds_read_b128 v[186:189], v149 offset:51200
	ds_read_b128 v[190:193], v149 offset:52224
	ds_read_b128 v[194:197], v149 offset:53248
	ds_read_b128 v[198:201], v149 offset:54272
	ds_read_b128 v[202:205], v149 offset:55296
	ds_read_b128 v[206:209], v149 offset:56320
	global_load_lds_dwordx4 v[210:211], off
	s_add_i32 m0, s30, 0x2000
	s_add_u32 s28, s28, 0x160080
	v_lshl_add_u64 v[210:211], v[212:213], 0, s[14:15]
	s_addc_u32 s29, s29, 0
	s_add_i32 s30, s62, s37
	global_load_lds_dwordx4 v[210:211], off
	v_lshl_add_u64 v[210:211], s[28:29], 0, v[128:129]
	s_mov_b32 m0, s30
	s_nop 0
	global_load_lds_dwordx4 v[210:211], off
	v_lshl_add_u64 v[210:211], s[28:29], 0, v[130:131]
	s_add_i32 m0, s30, 0x2000
	s_nop 0
	global_load_lds_dwordx4 v[210:211], off
	v_lshl_add_u64 v[210:211], v[214:215], 0, s[14:15]
	s_mov_b32 m0, s44
	s_nop 0
	global_load_lds_dwordx4 v[210:211], off
	v_lshl_add_u64 v[210:211], v[216:217], 0, s[14:15]
	s_mov_b32 m0, s45
	s_nop 0
	global_load_lds_dwordx4 v[210:211], off
	s_waitcnt vmcnt(8)
	s_waitcnt lgkmcnt(0)
	s_barrier
	s_setprio 1
	s_waitcnt lgkmcnt(0)
	v_mfma_f32_16x16x32_bf16 v[60:63], v[140:143], v[178:181], v[60:63]
	v_mfma_f32_16x16x32_bf16 v[56:59], v[154:157], v[178:181], v[56:59]
	v_mfma_f32_16x16x32_bf16 v[44:47], v[140:143], v[186:189], v[44:47]
	v_mfma_f32_16x16x32_bf16 v[40:43], v[154:157], v[186:189], v[40:43]
	v_mfma_f32_16x16x32_bf16 v[28:31], v[140:143], v[194:197], v[28:31]
	v_mfma_f32_16x16x32_bf16 v[24:27], v[154:157], v[194:197], v[24:27]
	v_mfma_f32_16x16x32_bf16 v[12:15], v[140:143], v[202:205], v[12:15]
	v_mfma_f32_16x16x32_bf16 v[8:11], v[154:157], v[202:205], v[8:11]
	v_mfma_f32_16x16x32_bf16 v[60:63], v[150:153], v[182:185], v[60:63]
	v_mfma_f32_16x16x32_bf16 v[56:59], v[158:161], v[182:185], v[56:59]
	v_mfma_f32_16x16x32_bf16 v[44:47], v[150:153], v[190:193], v[44:47]
	v_mfma_f32_16x16x32_bf16 v[40:43], v[158:161], v[190:193], v[40:43]
	v_mfma_f32_16x16x32_bf16 v[28:31], v[150:153], v[198:201], v[28:31]
	v_mfma_f32_16x16x32_bf16 v[24:27], v[158:161], v[198:201], v[24:27]
	v_mfma_f32_16x16x32_bf16 v[12:15], v[150:153], v[206:209], v[12:15]
	v_mfma_f32_16x16x32_bf16 v[8:11], v[158:161], v[206:209], v[8:11]
	s_setprio 0
	s_setprio 1
	v_mfma_f32_16x16x32_bf16 v[52:55], v[162:165], v[178:181], v[52:55]
	v_mfma_f32_16x16x32_bf16 v[48:51], v[170:173], v[178:181], v[48:51]
	v_mfma_f32_16x16x32_bf16 v[36:39], v[162:165], v[186:189], v[36:39]
	v_mfma_f32_16x16x32_bf16 v[32:35], v[170:173], v[186:189], v[32:35]
	v_mfma_f32_16x16x32_bf16 v[20:23], v[162:165], v[194:197], v[20:23]
	v_mfma_f32_16x16x32_bf16 v[16:19], v[170:173], v[194:197], v[16:19]
	v_mfma_f32_16x16x32_bf16 v[4:7], v[162:165], v[202:205], v[4:7]
	v_mfma_f32_16x16x32_bf16 v[0:3], v[170:173], v[202:205], v[0:3]
	v_mfma_f32_16x16x32_bf16 v[52:55], v[166:169], v[182:185], v[52:55]
	v_mfma_f32_16x16x32_bf16 v[48:51], v[174:177], v[182:185], v[48:51]
	v_mfma_f32_16x16x32_bf16 v[36:39], v[166:169], v[190:193], v[36:39]
	v_mfma_f32_16x16x32_bf16 v[32:35], v[174:177], v[190:193], v[32:35]
	v_mfma_f32_16x16x32_bf16 v[20:23], v[166:169], v[198:201], v[20:23]
	v_mfma_f32_16x16x32_bf16 v[16:19], v[174:177], v[198:201], v[16:19]
	v_mfma_f32_16x16x32_bf16 v[4:7], v[166:169], v[206:209], v[4:7]
	v_mfma_f32_16x16x32_bf16 v[0:3], v[174:177], v[206:209], v[0:3]
	s_setprio 0
	s_add_i32 s60, s60, 2
	s_add_u32 s26, s26, 0x100
	s_addc_u32 s27, s27, 0
	s_add_u32 s58, s58, 0x100
	s_addc_u32 s59, s59, 0
	s_cmpk_gt_u32 s60, 0x55
	s_barrier
	s_cbranch_scc0 .LBB0_898
	s_and_b64 vcc, exec, s[16:17]
	s_cbranch_vccz .LBB0_901
	s_barrier
